# P7 MLP-up tail: the 32 tiles of the partial 5th round split over 64 workgroups (two per tile, each runs a K-loop copy with half the MFMAs/LDS reads and stores half the accumulators)
# baseline (speedup 1.0000x reference)
;     ...
;     for (int i = F.tid; i < 1024; i += NWAVES * 64) {
;         gl[i] = gw_[i];
; #pragma unroll
;         for (int cnd = 0; cnd < 3; ++cnd) {
;             float sh, sc;
;             if (from_partials) { sh = ada_b[layer * 6144 + offsh + i]; sc = ada_b[layer * 6144 + offsc + i];
;                 float ph[ADA_KS], pc[ADA_KS];
; #pragma unroll
;                 for (int ks = 0; ks < ADA_KS; ++ks) { const float* p = modp + ((size_t)(ks * 2 + layer) * 3 + cnd) * 6144; ph[ks] = p[offsh + i]; pc[ks] = p[offsc + i]; }
; #pragma unroll
;                 for (int ks = 0; ks < ADA_KS; ++ks) { sh += ph[ks]; sc += pc[ks]; } }
;             else { sh = mod[(layer * 3 + cnd) * 6144 + offsh + i]; sc = mod[(layer * 3 + cnd) * 6144 + offsc + i]; }
;             scl[cnd * 1024 + i] = 1.f + sc; shl[cnd * 1024 + i] = sh;
;         }
;     }
.LBB0_153:
	v_lshlrev_b32_e32 v220, 2, v2
	v_lshlrev_b32_e32 v221, 2, v3
	global_load_dword v236, v220, s[4:5]
	global_load_dword v237, v221, s[4:5]
	v_add_u32_e32 v222, s12, v220
	v_add_u32_e32 v223, s12, v221
	global_load_dword v228, v222, s[8:9] offset:-4096
	global_load_dword v229, v223, s[8:9] offset:-4096
	global_load_dword v230, v222, s[8:9]
	global_load_dword v231, v223, s[8:9]
	v_add_u32_e32 v222, s13, v220
	v_add_u32_e32 v223, s13, v221
	global_load_dword v232, v222, s[8:9] offset:-4096
	global_load_dword v233, v223, s[8:9] offset:-4096
	global_load_dword v234, v222, s[8:9]
	global_load_dword v235, v223, s[8:9]
	v_add_u32_e32 v222, s14, v220
	v_add_u32_e32 v223, s14, v221
	global_load_dword v238, v222, s[8:9] offset:-4096
	global_load_dword v239, v223, s[8:9] offset:-4096
	global_load_dword v240, v222, s[8:9]
	global_load_dword v241, v223, s[8:9]
	v_add_u32_e32 v7, -2, v7
	v_add_u32_e32 v224, 0x400, v2
	v_add_u32_e32 v225, 0x400, v3
	v_lshl_add_u32 v226, v224, 2, 0
	v_lshl_add_u32 v227, v225, 2, 0
	v_cmp_eq_u32_e32 vcc, 0, v7
	s_or_b64 s[10:11], vcc, s[10:11]
	s_waitcnt vmcnt(0)
	ds_write2st64_b32 v8, v236, v237 offset1:8
	v_add_f32_e32 v230, 1.0, v230
	v_add_f32_e32 v231, 1.0, v231
	ds_write2st64_b32 v8, v230, v231 offset0:16 offset1:24
	ds_write2st64_b32 v8, v228, v229 offset0:64 offset1:72
	v_add_f32_e32 v234, 1.0, v234
	v_add_f32_e32 v235, 1.0, v235
	ds_write_b32 v226, v234 offset:4096
	ds_write_b32 v227, v235 offset:4096
	ds_write_b32 v226, v232 offset:16384
	ds_write_b32 v227, v233 offset:16384
	v_add_f32_e32 v240, 1.0, v240
	v_add_f32_e32 v241, 1.0, v241
	ds_write_b32 v220, v240 offset:12288
	ds_write_b32 v221, v241 offset:12288
	ds_write_b32 v220, v238 offset:24576
	ds_write_b32 v221, v239 offset:24576
	v_add_u32_e32 v8, 0x1000, v8
	v_mov_b32_e32 v2, v224
	v_mov_b32_e32 v3, v225
	s_andn2_b64 exec, exec, s[10:11]
	s_cbranch_execnz .LBB0_153
	s_nop 0
	s_nop 0
	s_nop 0
	s_nop 0
	s_nop 0
	s_nop 0
	s_nop 0
	s_nop 0
	s_or_b64 exec, exec, s[10:11]
	v_cmp_ne_u32_e32 vcc, v0, v6
	v_lshl_add_u32 v2, v6, 9, v170
	s_orn2_b64 s[8:9], vcc, exec

; #define PG8_STAGE(bufoff, gbase, voff) do { _Pragma("unroll") for (int _i = 0; _i < 2; ++_i) { unsigned keep_; \
;         asm volatile("s_mov_b32 %0, m0\n\ts_mov_b32 m0, %3\n\ts_nop 0\n\tglobal_load_lds_dwordx4 %1, %2\n\ts_mov_b32 m0, %0" : "=&s"(keep_) : "v"((voff)[_i]), "s"((const char*)(gbase)), "s"(ldsb + (unsigned)((bufoff) + _i * 8192)) : "memory"); } } while (0)
; #define PG8_WAIT_V(n) asm volatile("s_waitcnt vmcnt(" #n ")" ::: "memory")
; #define PG8_BAR __builtin_amdgcn_s_barrier()
;     __host__ __device__ bool next(int i, Unit& u) const {
;     ...
;         int wgid = (int)L; { const int q = nwg / NXCD, r = nwg % NXCD, xcd = wgid % NXCD, off = wgid / NXCD; wgid = (xcd < r ? xcd * (q + 1) : r * (q + 1) + (xcd - r) * q) + off; }
;         const int nig = WGM * nN, gid = wgid / nig, fm = gid * WGM, gsz = (nM - fm) < WGM ? (nM - fm) : WGM;
;         u.pm = fm + ((wgid % nig) % gsz); u.pn = (wgid % nig) / gsz; u.kinfo = ntK << 8; return true;
; template <class Epi, class Sched, bool ALIGN_EPI = false, bool SP2 = false, bool MX8 = false>
; __device__ __forceinline__ void gemm_phase(PG8_LAS unsigned char* lds, const Gemm g, const Sched& S, const Epi& E, const int tid) {
;     ...
;         PG8_WAIT_V(2); PG8_BAR;
;         PG8_STAGE(PG8_SB(1, 0), cB + kstep, voffB); PG8_STAGE(PG8_SA(1, 0), cA + kstep, voffA); PG8_STAGE(PG8_SB(1, 1), cB + hstepB + kstep, voffB);
;         PG8_WAIT_V(6); PG8_BAR;
.LBB0_815:
	v_bfe_u32 v208, v170, 4, 2
	v_and_b32_e32 v207, 15, v170
	v_lshlrev_b32_e32 v0, 4, v208
	v_lshlrev_b32_e32 v2, 2, v170
	s_and_b32 s80, s12, 3
	v_lshl_or_b32 v0, v207, 6, v0
	s_lshl_b32 s12, s11, 13
	v_and_b32_e32 v2, 32, v2
	s_lshl_b32 s81, s11, 6
	v_bitop3_b32 v3, v0, s12, v2 bitop3:0xde
	s_lshl_b32 s4, s80, 5
	s_lshl_b32 s12, s80, 12
	v_bitop3_b32 v0, s12, v0, v2 bitop3:0xf6
	s_add_u32 s12, s2, 0x80
	s_waitcnt vmcnt(2)
	s_barrier
	s_addc_u32 s13, s3, 0
	s_add_i32 s85, s46, 0x18000
	s_mov_b32 s14, m0
	s_mov_b32 m0, s85
	s_nop 0
	global_load_lds_dwordx4 v206, s[12:13]
	s_mov_b32 m0, s14
	s_add_i32 s86, s46, 0x1a000
	s_mov_b32 s14, m0
	s_mov_b32 m0, s86
	s_nop 0
	global_load_lds_dwordx4 v204, s[12:13]
	s_mov_b32 m0, s14
	s_add_u32 s12, s8, 0x80
	s_addc_u32 s13, s9, 0
	s_add_i32 s87, s46, 0x8000
	s_add_i32 s88, s46, 0xa000
	s_add_u32 s6, s6, 0x80
	s_addc_u32 s7, s7, 0
	s_add_i32 s89, s46, 0x1c000
	s_add_i32 s92, s46, 0x1e000
	s_add_i32 s93, s46, 0xc000
	s_cmpk_lt_u32 s10, 0x100
	v_writelane_b32 v243, s4, 33
	s_cselect_b64 s[90:91], -1, 0
	s_lshl_b32 s4, s80, 6
	v_writelane_b32 v243, s4, 44
	s_mov_b32 s14, m0
	s_mov_b32 m0, s87
	s_nop 0
	global_load_lds_dwordx4 v205, s[12:13]
	s_mov_b32 m0, s14
	s_not_b32 s10, s73
	v_readlane_b32 s4, v243, 9
	s_mov_b32 s14, m0
	s_mov_b32 m0, s88
	s_nop 0
	global_load_lds_dwordx4 v171, s[12:13]
	s_mov_b32 m0, s14
	v_readlane_b32 s5, v243, 10
	s_mov_b32 s12, m0
	s_mov_b32 m0, s89
	s_nop 0
	global_load_lds_dwordx4 v206, s[6:7]
	s_mov_b32 m0, s12
	s_mov_b32 s19, s5
	s_mov_b32 s12, m0
	s_mov_b32 m0, s92
	s_nop 0
	global_load_lds_dwordx4 v204, s[6:7]
	s_mov_b32 m0, s12
	s_mov_b32 s51, s5
	s_lshl_b64 s[4:5], s[18:19], s16
	v_readlane_b32 s13, v243, 18
	v_writelane_b32 v243, s4, 51
	s_lshl_b32 s12, -1, s16
	s_lshl_b32 s6, s11, 12
	v_writelane_b32 v243, s5, 52
	s_not_b32 s4, s12
	v_writelane_b32 v243, s4, 59
	v_writelane_b32 v243, s16, 47
	s_lshr_b32 s4, s17, s16
	v_writelane_b32 v243, s4, 61
	s_lshl_b32 s12, s4, 8
	s_lshr_b32 s4, s50, 3
	s_add_i32 s11, s50, s13
	v_writelane_b32 v243, s4, 49
	s_add_i32 s4, s4, 1
	s_lshl_b32 s7, s80, 10
	s_add_i32 s95, s46, 0xe000
	s_ashr_i32 s96, s13, 31
	s_ashr_i32 s97, s73, 31
	s_add_i32 s11, s11, s10
	s_add_i32 s10, s73, s13
	s_and_b32 s53, s50, 6
	v_writelane_b32 v243, s4, 45
	s_lshl_b32 s62, s48, 3
	s_lshl_b32 s4, s54, 2
	s_add_u32 s54, s28, 0x2000
	s_addc_u32 s55, s29, 0
	s_add_i32 s6, s6, 0
	s_add_i32 s84, s6, s7
	s_xor_b32 s6, s11, s13
	s_abs_i32 s7, s11
	s_abs_i32 s11, s13
	v_cvt_f32_u32_e32 v2, s11
	v_writelane_b32 v243, s4, 42
	s_or_b32 s4, s12, 0x10000
	s_sub_i32 s12, 0, s11
	v_rcp_iflag_f32_e32 v2, v2
	s_add_i32 s84, s84, 0x21000
	s_ashr_i32 s6, s6, 31
	v_writelane_b32 v243, s4, 62
	v_mul_f32_e32 v2, 0x4f7ffffe, v2
	v_cvt_u32_f32_e32 v2, v2
	s_waitcnt vmcnt(6)
	s_mov_b32 s40, 0
	v_add_u32_e32 v209, 0, v0
	v_readfirstlane_b32 s13, v2
	s_mul_i32 s12, s12, s13
	s_mul_hi_u32 s12, s13, s12
	s_add_i32 s13, s13, s12
	s_mul_hi_u32 s12, s7, s13
	s_mul_i32 s14, s12, s11
	s_sub_i32 s7, s7, s14
	s_add_i32 s14, s12, 1
	s_sub_i32 s15, s7, s11
	s_cmp_ge_u32 s7, s11
	s_cselect_b32 s12, s14, s12
	s_cselect_b32 s7, s15, s7
	s_add_i32 s14, s12, 1
	s_cmp_ge_u32 s7, s11
	s_cselect_b32 s7, s14, s12
	s_xor_b32 s7, s7, s6
	s_sub_i32 s6, s7, s6
	s_and_b64 s[0:1], s[0:1], exec
	s_cselect_b32 s0, s6, 0
	v_writelane_b32 v243, s0, 63
	s_mul_hi_u32 s0, s50, s13
	s_mul_i32 s0, s0, s11
	s_sub_i32 s0, s50, s0
	s_sub_i32 s1, s0, s11
	s_cmp_ge_u32 s0, s11
	s_cselect_b32 s0, s1, s0
	s_sub_i32 s1, s0, s11
	s_cmp_ge_u32 s0, s11
	s_cselect_b32 s0, s1, s0
	v_cvt_f32_u32_e32 v2, s48
	s_sub_i32 s0, s10, s0
	s_ashr_i32 s1, s0, 31
	s_abs_i32 s0, s0
	s_mul_hi_u32 s6, s0, s13
	s_mul_i32 s6, s6, s11
	v_rcp_iflag_f32_e32 v2, v2
	s_sub_i32 s0, s0, s6
	s_sub_i32 s6, s0, s11
	s_cmp_ge_u32 s0, s11
	s_cselect_b32 s0, s6, s0
	v_mul_f32_e32 v2, 0x4f7ffffe, v2
	s_sub_i32 s6, s0, s11
	v_cvt_u32_f32_e32 v2, v2
	s_cmp_ge_u32 s0, s11
	s_cselect_b32 s0, s6, s0
	s_xor_b32 s0, s0, s1
	s_sub_i32 s0, s0, s1
	v_readfirstlane_b32 s1, v2
	v_cvt_f32_u32_e32 v2, s62
	v_writelane_b32 v242, s0, 0
	s_ashr_i32 s0, s0, 31
	v_writelane_b32 v242, s0, 1
	v_rcp_iflag_f32_e32 v2, v2
	s_sub_i32 s0, 0, s48
	s_mul_i32 s0, s0, s1
	s_mul_hi_u32 s0, s1, s0
	v_mul_f32_e32 v2, 0x4f7ffffe, v2
	v_cvt_u32_f32_e32 v2, v2
	s_add_i32 s0, s1, s0
	v_writelane_b32 v242, s0, 2
	s_sub_i32 s0, 0, s62
	v_readfirstlane_b32 s1, v2
	s_mul_i32 s0, s0, s1
	s_mul_hi_u32 s0, s1, s0
	s_add_i32 s0, s1, s0
	v_add_u32_e32 v210, 0, v3
	s_mov_b32 s64, 0xf800000
	s_barrier
	v_writelane_b32 v243, s0, 43
	s_mov_b32 s32, 0
	s_mov_b32 s99, 0
	s_branch .LBB0_818

;     __device__ __forceinline__ static float xsh(float v, int mask, int lane) { return __builtin_bit_cast(float, __builtin_amdgcn_ds_bpermute((lane ^ mask) << 2, __builtin_bit_cast(int, v))); }
;     __host__ __device__ bool next(int i, Unit& u) const {
;         const long L = (long)i * G + c;
;         if (L >= nwg) {
;             if (xtiles == 0) return false;
;             const int nb = (nwg - c + G - 1) / G;
;             const int nbc = c < nwg ? nb : 0;
;             const long e = (long)(i - nbc) * G + ((c + G - (nwg % G)) % G);
;             if (e >= ((long)xtiles << xsh)) return false;
;             const int tile = (int)(e >> xsh), ks = (int)e & ((1 << xsh) - 1), xnt = ntK >> xsh;
;             u.pm = nM + tile / nN; u.pn = tile % nN; u.kinfo = (ks * xnt) | (xnt << 8) | (1 << 16); return true;
;         }
;         int wgid = (int)L; { const int q = nwg / NXCD, r = nwg % NXCD, xcd = wgid % NXCD, off = wgid / NXCD; wgid = (xcd < r ? xcd * (q + 1) : r * (q + 1) + (xcd - r) * q) + off; }
;         const int nig = WGM * nN, gid = wgid / nig, fm = gid * WGM, gsz = (nM - fm) < WGM ? (nM - fm) : WGM;
;         u.pm = fm + ((wgid % nig) % gsz); u.pn = (wgid % nig) / gsz; u.kinfo = ntK << 8; return true;
; template <class Epi, class Sched, bool ALIGN_EPI = false, bool SP2 = false, bool MX8 = false>
; __device__ __forceinline__ void gemm_phase(PG8_LAS unsigned char* lds, const Gemm g, const Sched& S, const Epi& E, const int tid) {
;     ...
;         cur = nxt; cA = nA; cB = nB; ++ui;
.LBB0_817:
	s_andn2_b64 vcc, exec, s[0:1]
	s_mov_b32 s63, s41
	s_mov_b32 s42, s94
	s_mov_b32 s43, s52
	s_mov_b32 s32, s99
	s_mov_b64 s[2:3], s[70:71]
	s_mov_b64 s[8:9], s[66:67]
	s_cbranch_vccz .LBB0_1105
.LBB0_818:
	s_add_i32 s40, s40, 1
	v_readlane_b32 s4, v243, 18
	s_mul_i32 s0, s40, s96
	s_mul_hi_u32 s1, s40, s4
	s_add_i32 s1, s1, s0
	s_mul_i32 s0, s40, s4
	s_add_u32 s0, s0, s73
	s_addc_u32 s1, s1, s97
	s_mov_b32 s99, 0
	s_cmp_lg_u32 s49, 1
	s_cbranch_scc1 .Lht_done
	s_cmpk_lg_u32 s50, 0x420
	s_cbranch_scc1 .Lht_done
	s_cmp_lg_u32 s1, 0
	s_cbranch_scc1 .Lht_done
	s_cmpk_lt_u32 s0, 0x400
	s_cbranch_scc1 .Lht_done
	s_cmpk_ge_u32 s0, 0x440
	s_cbranch_scc1 .Lht_done
	s_sub_u32 s98, s0, 0x400
	s_and_b32 s99, s98, 1
	s_add_u32 s99, s99, 1
	s_lshr_b32 s98, s98, 1
	s_add_u32 s0, s98, 0x400
.Lht_done:
	s_waitcnt vmcnt(0)
	v_mov_b64_e32 v[2:3], s[50:51]
	v_cmp_lt_i64_e32 vcc, s[0:1], v[2:3]
	s_mov_b64 s[6:7], -1
	s_cbranch_vccnz .LBB0_823
	v_readlane_b32 s4, v243, 36
	v_readlane_b32 s5, v243, 37
	s_and_b64 vcc, exec, s[4:5]
	s_mov_b64 s[6:7], 0
	s_cbranch_vccnz .LBB0_822
	v_readlane_b32 s1, v243, 63
	s_sub_i32 s1, s40, s1
	v_readlane_b32 s4, v243, 18
	s_mul_hi_i32 s10, s1, s4
	s_mul_i32 s1, s1, s4
	v_readlane_b32 s4, v242, 0
	s_add_u32 s12, s1, s4
	v_readlane_b32 s4, v243, 51
	v_readlane_b32 s1, v242, 1
	v_readlane_b32 s5, v243, 52
	s_addc_u32 s13, s10, s1
	s_mov_b64 s[10:11], 0
	v_mov_b64_e32 v[2:3], s[4:5]
	v_cmp_ge_i64_e32 vcc, s[12:13], v[2:3]
	s_cbranch_vccnz .LBB0_823
	v_readlane_b32 s1, v243, 47
	s_ashr_i64 s[10:11], s[12:13], s1
	v_readlane_b32 s1, v243, 59
	s_and_b32 s1, s12, s1
	s_abs_i32 s12, s10
	v_readlane_b32 s4, v242, 2
	s_mul_hi_u32 s13, s12, s4
	s_mul_i32 s14, s13, s48
	s_sub_i32 s12, s12, s14
	s_ashr_i32 s11, s10, 31
	s_add_i32 s14, s13, 1
	s_sub_i32 s15, s12, s48
	s_cmp_ge_u32 s12, s48
	s_cselect_b32 s13, s14, s13
	s_cselect_b32 s12, s15, s12
	s_add_i32 s14, s13, 1
	s_cmp_ge_u32 s12, s48
	s_cselect_b32 s12, s14, s13
	s_xor_b32 s12, s12, s11
	s_sub_i32 s11, s12, s11
	v_readlane_b32 s4, v243, 61
	s_add_i32 s52, s11, s69
	s_mul_i32 s11, s11, s48
	s_mul_i32 s1, s1, s4
	v_readlane_b32 s4, v243, 62
	s_sub_i32 s94, s10, s11
	s_or_b32 s41, s1, s4
	s_mov_b64 s[10:11], -1
	s_branch .LBB0_823

; template <class Epi, class Sched, bool ALIGN_EPI = false, bool SP2 = false, bool MX8 = false>
; __device__ __forceinline__ void gemm_phase(PG8_LAS unsigned char* lds, const Gemm g, const Sched& S, const Epi& E, const int tid) {
;     ...
; #pragma unroll
;         for (int a = 0; a < 2; ++a)
; #pragma unroll
;             for (int b = 0; b < 2; ++b)
; #pragma unroll
;                 for (int m = 0; m < 4; ++m)
; #pragma unroll
;                     for (int n = 0; n < 2; ++n) acc[a][b][m][n] = (f32x4){0.f, 0.f, 0.f, 0.f};
.LBB0_832:
	s_add_u32 s0, s8, s56
	s_addc_u32 s1, s9, s57
	s_add_i32 s13, s12, -2
	s_add_u32 s14, s8, 0x100
	s_addc_u32 s15, s9, 0
	s_add_u32 s16, s2, 0x100
	s_addc_u32 s17, s3, 0
	s_add_u32 s0, s0, 0x80
	v_mov_b32_e32 v18, 0
	s_addc_u32 s1, s1, 0
	s_mov_b32 s2, 0
	v_mov_b32_e32 v19, v18
	v_mov_b32_e32 v20, v18
	v_mov_b32_e32 v21, v18
	v_mov_b32_e32 v22, v18
	v_mov_b32_e32 v23, v18
	v_mov_b32_e32 v24, v18
	v_mov_b32_e32 v25, v18
	v_mov_b32_e32 v34, v18
	v_mov_b32_e32 v35, v18
	v_mov_b32_e32 v36, v18
	v_mov_b32_e32 v37, v18
	v_mov_b32_e32 v38, v18
	v_mov_b32_e32 v39, v18
	v_mov_b32_e32 v40, v18
	v_mov_b32_e32 v41, v18
	v_mov_b32_e32 v50, v18
	v_mov_b32_e32 v51, v18
	v_mov_b32_e32 v52, v18
	v_mov_b32_e32 v53, v18
	v_mov_b32_e32 v54, v18
	v_mov_b32_e32 v55, v18
	v_mov_b32_e32 v56, v18
	v_mov_b32_e32 v57, v18
	v_mov_b32_e32 v66, v18
	v_mov_b32_e32 v67, v18
	v_mov_b32_e32 v68, v18
	v_mov_b32_e32 v69, v18
	v_mov_b32_e32 v70, v18
	v_mov_b32_e32 v71, v18
	v_mov_b32_e32 v72, v18
	v_mov_b32_e32 v73, v18
	v_mov_b32_e32 v26, v18
	v_mov_b32_e32 v27, v18
	v_mov_b32_e32 v28, v18
	v_mov_b32_e32 v29, v18
	v_mov_b32_e32 v30, v18
	v_mov_b32_e32 v31, v18
	v_mov_b32_e32 v32, v18
	v_mov_b32_e32 v33, v18
	v_mov_b32_e32 v42, v18
	v_mov_b32_e32 v43, v18
	v_mov_b32_e32 v44, v18
	v_mov_b32_e32 v45, v18
	v_mov_b32_e32 v46, v18
	v_mov_b32_e32 v47, v18
	v_mov_b32_e32 v48, v18
	v_mov_b32_e32 v49, v18
	v_mov_b32_e32 v58, v18
	v_mov_b32_e32 v59, v18
	v_mov_b32_e32 v60, v18
	v_mov_b32_e32 v61, v18
	v_mov_b32_e32 v62, v18
	v_mov_b32_e32 v63, v18
	v_mov_b32_e32 v64, v18
	v_mov_b32_e32 v65, v18
	v_mov_b32_e32 v74, v18
	v_mov_b32_e32 v75, v18
	v_mov_b32_e32 v76, v18
	v_mov_b32_e32 v77, v18
	v_mov_b32_e32 v78, v18
	v_mov_b32_e32 v79, v18
	v_mov_b32_e32 v80, v18
	v_mov_b32_e32 v81, v18
	v_mov_b32_e32 v82, v18
	v_mov_b32_e32 v83, v18
	v_mov_b32_e32 v84, v18
	v_mov_b32_e32 v85, v18
	v_mov_b32_e32 v86, v18
	v_mov_b32_e32 v87, v18
	v_mov_b32_e32 v88, v18
	v_mov_b32_e32 v89, v18
	v_mov_b32_e32 v98, v18
	v_mov_b32_e32 v99, v18
	v_mov_b32_e32 v100, v18
	v_mov_b32_e32 v101, v18
	v_mov_b32_e32 v102, v18
	v_mov_b32_e32 v103, v18
	v_mov_b32_e32 v104, v18
	v_mov_b32_e32 v105, v18
	v_mov_b32_e32 v114, v18
	v_mov_b32_e32 v115, v18
	v_mov_b32_e32 v116, v18
	v_mov_b32_e32 v117, v18
	v_mov_b32_e32 v118, v18
	v_mov_b32_e32 v119, v18
	v_mov_b32_e32 v120, v18
	v_mov_b32_e32 v121, v18
	v_mov_b32_e32 v130, v18
	v_mov_b32_e32 v131, v18
	v_mov_b32_e32 v132, v18
	v_mov_b32_e32 v133, v18
	v_mov_b32_e32 v134, v18
	v_mov_b32_e32 v135, v18
	v_mov_b32_e32 v136, v18
	v_mov_b32_e32 v137, v18
	v_mov_b32_e32 v90, v18
	v_mov_b32_e32 v91, v18
	v_mov_b32_e32 v92, v18
	v_mov_b32_e32 v93, v18
	v_mov_b32_e32 v94, v18
	v_mov_b32_e32 v95, v18
	v_mov_b32_e32 v96, v18
	v_mov_b32_e32 v97, v18
	v_mov_b32_e32 v106, v18
	v_mov_b32_e32 v107, v18
	v_mov_b32_e32 v108, v18
	v_mov_b32_e32 v109, v18
	v_mov_b32_e32 v110, v18
	v_mov_b32_e32 v111, v18
	v_mov_b32_e32 v112, v18
	v_mov_b32_e32 v113, v18
	v_mov_b32_e32 v122, v18
	v_mov_b32_e32 v123, v18
	v_mov_b32_e32 v124, v18
	v_mov_b32_e32 v125, v18
	v_mov_b32_e32 v126, v18
	v_mov_b32_e32 v127, v18
	v_mov_b32_e32 v128, v18
	v_mov_b32_e32 v129, v18
	v_mov_b32_e32 v142, v18
	v_mov_b32_e32 v143, v18
	v_mov_b32_e32 v144, v18
	v_mov_b32_e32 v145, v18
	v_mov_b32_e32 v138, v18
	v_mov_b32_e32 v139, v18
	v_mov_b32_e32 v140, v18
	v_mov_b32_e32 v141, v18
	s_cmp_eq_u32 s32, 1
	s_cbranch_scc1 .Lht_loopA
	s_cmp_eq_u32 s32, 2
	s_cbranch_scc1 .Lht_loopB

; #define PG8_BAR __builtin_amdgcn_s_barrier()
; template <class Epi, class Sched, bool ALIGN_EPI = false, bool SP2 = false, bool MX8 = false>
; __device__ __forceinline__ void gemm_phase(PG8_LAS unsigned char* lds, const Gemm g, const Sched& S, const Epi& E, const int tid) {
;     ...
;         if constexpr (ALIGN_EPI) { if (wr == 0) PG8_BAR; }
.Lht_exit:
	s_and_b64 vcc, exec, s[90:91]
	s_cbranch_vccz .LBB0_836

;     __device__ __forceinline__ void operator()(const f32x4 (&acc)[2][2][4][2], const Unit& u, int wr, int wc, int fr, int fq) const {
;     ...
;         if (mode == 1) {
;             bf16_t* O = (bf16_t*)out;
;             const int row0 = u.pm * BM + wr * 64 + fr, col0 = u.pn * BM + wc * 32 + 8 * fq;
; #pragma unroll
;             for (int ai = 0; ai < 2; ++ai)
; #pragma unroll
;                 for (int m = 0; m < 4; ++m) { bf16_t* rowp = O + (size_t)(row0 + ai * HALF + m * 16) * ldc + col0;
; #pragma unroll
;                     for (int bj = 0; bj < 2; ++bj) { f32x4 v0 = acc[ai][bj][m][0], v1 = acc[ai][bj][m][1];
;                         if (relu2) {
; #pragma unroll
;                             for (int e = 0; e < 4; ++e) { float a = fmaxf(v0[e], 0.f), b = fmaxf(v1[e], 0.f); v0[e] = a * a; v1[e] = b * b; } }
.LBB0_1068:
	s_andn2_b64 vcc, exec, s[0:1]
	s_cbranch_vccnz .LBB0_1102
	s_cmp_lg_u32 s32, 0
	s_cbranch_scc1 .Lht_epi
	v_cndmask_b32_e64 v0, 0, 1, s[44:45]
	v_cmp_ne_u32_e64 s[8:9], 1, v0
	s_andn2_b64 vcc, exec, s[44:45]
	s_cbranch_vccnz .LBB0_1071
	v_max_f32_e32 v0, v138, v138
	s_waitcnt vmcnt(0)
	v_max_f32_e32 v2, 0, v0
	v_max_f32_e32 v0, v142, v142
	v_max_f32_e32 v4, 0, v0
	v_max_f32_e32 v0, v139, v139
	v_max_f32_e32 v3, 0, v0
	v_max_f32_e32 v0, v143, v143
	v_max_f32_e32 v5, 0, v0
	v_max_f32_e32 v0, v140, v140
	v_max_f32_e32 v6, 0, v0
	v_max_f32_e32 v0, v144, v144
	v_max_f32_e32 v8, 0, v0
	v_max_f32_e32 v0, v141, v141
	v_max_f32_e32 v7, 0, v0
	v_max_f32_e32 v0, v145, v145
	v_max_f32_e32 v9, 0, v0
	v_pk_mul_f32 v[138:139], v[2:3], v[2:3]
	v_pk_mul_f32 v[140:141], v[6:7], v[6:7]
	v_pk_mul_f32 v[142:143], v[4:5], v[4:5]
	v_pk_mul_f32 v[144:145], v[8:9], v[8:9]

; #define PG8_STAGE(bufoff, gbase, voff) do { _Pragma("unroll") for (int _i = 0; _i < 2; ++_i) { unsigned keep_; \
;         asm volatile("s_mov_b32 %0, m0\n\ts_mov_b32 m0, %3\n\ts_nop 0\n\tglobal_load_lds_dwordx4 %1, %2\n\ts_mov_b32 m0, %0" : "=&s"(keep_) : "v"((voff)[_i]), "s"((const char*)(gbase)), "s"(ldsb + (unsigned)((bufoff) + _i * 8192)) : "memory"); } } while (0)
; #define PG8_LDA(dst, b, h) do { _Pragma("unroll") for (int m = 0; m < 4; ++m) _Pragma("unroll") for (int k = 0; k < 2; ++k) dst[m][k] = *(const PG8_LAS bf16x8*)(lds + PG8_SA(b, h) + aoff + m * 2048 + k * 1024); } while (0)
; #define PG8_LDB(dst, b, h) do { _Pragma("unroll") for (int n = 0; n < 2; ++n) _Pragma("unroll") for (int k = 0; k < 2; ++k) dst[n][k] = *(const PG8_LAS bf16x8*)(lds + PG8_SB(b, h) + boff + n * 2048 + k * 1024); } while (0)
; #define PG8_WAIT_V(n) asm volatile("s_waitcnt vmcnt(" #n ")" ::: "memory")
; #define PG8_WAIT_L(n) asm volatile("s_waitcnt lgkmcnt(" #n ")" ::: "memory")
; #define PG8_BAR __builtin_amdgcn_s_barrier()
; #define PG8_SCHED __builtin_amdgcn_sched_barrier(0)
; template <class Epi, class Sched, bool ALIGN_EPI = false, bool SP2 = false, bool MX8 = false>
; __device__ __forceinline__ void gemm_phase(PG8_LAS unsigned char* lds, const Gemm g, const Sched& S, const Epi& E, const int tid) {
;     ...
;             PG8_LDB(B0, 0, 0); PG8_LDB(B1, 0, 1); PG8_SCHED; PG8_LDA(At, 0, 0); PG8_STAGE(PG8_SA(1, 1), a1 + hstep, voffA);
;             PG8_WAIT_V(8); PG8_WAIT_L(0); PG8_BAR; PG8_MMA(0, 0, At, B0); PG8_MMA(0, 1, At, B1); PG8_BAR; PG8_SCHED;
;             PG8_LDA(At, 0, 1); PG8_STAGE(PG8_SB(0, 0), b2, voffB); PG8_STAGE(PG8_SB(0, 1), b2 + hstepB, voffB); PG8_STAGE(PG8_SA(0, 0), a2, voffA);
;             PG8_WAIT_V(8); PG8_WAIT_L(0); PG8_BAR; PG8_MMA(1, 0, At, B0); PG8_MMA(1, 1, At, B1); PG8_BAR; PG8_SCHED;
;             PG8_LDB(B0, 1, 0); PG8_LDB(B1, 1, 1); PG8_SCHED; PG8_LDA(At, 1, 0); PG8_STAGE(PG8_SA(0, 1), a2 + hstep, voffA);
;             PG8_WAIT_V(8); PG8_WAIT_L(0); PG8_BAR; PG8_MMA(0, 0, At, B0); PG8_MMA(0, 1, At, B1); PG8_BAR; PG8_SCHED;
;             PG8_LDA(At, 1, 1); PG8_STAGE(PG8_SB(1, 0), b3, voffB); PG8_STAGE(PG8_SB(1, 1), b3 + hstepB, voffB); PG8_STAGE(PG8_SA(1, 0), a3, voffA);
;             PG8_WAIT_V(8); PG8_WAIT_L(0); PG8_BAR; PG8_MMA(1, 0, At, B0); PG8_MMA(1, 1, At, B1); PG8_BAR; PG8_SCHED;
.Lht_loopA:
	v_add_u32_e32 v0, 0x10000, v209
	ds_read_b128 v[2:5], v0
	ds_read_b128 v[6:9], v0 offset:1024
	ds_read_b128 v[10:13], v0 offset:2048
	ds_read_b128 v[14:17], v0 offset:3072
	v_add_u32_e32 v0, 0x14000, v209
	s_add_i32 s18, s2, 2
	s_cmp_eq_u32 s13, s2
	s_cselect_b32 s10, s66, s14
	s_cselect_b32 s11, s67, s15
	s_cselect_b32 s8, s70, s16
	s_cselect_b32 s9, s71, s17
	s_add_u32 s2, s10, 0x80
	s_addc_u32 s3, s11, 0
	ds_read_b128 v[162:165], v210
	ds_read_b128 v[166:169], v210 offset:1024
	ds_read_b128 v[174:177], v210 offset:2048
	ds_read_b128 v[178:181], v210 offset:3072
	ds_read_b128 v[182:185], v210 offset:4096
	ds_read_b128 v[212:215], v210 offset:5120
	ds_read_b128 v[216:219], v210 offset:6144
	ds_read_b128 v[220:223], v210 offset:7168
	s_mov_b32 s19, m0
	s_mov_b32 m0, s93
	s_nop 0
	global_load_lds_dwordx4 v205, s[0:1]
	s_mov_b32 m0, s19
	s_nop 0
	s_mov_b32 s19, m0
	s_mov_b32 m0, s95
	s_nop 0
	global_load_lds_dwordx4 v171, s[0:1]
	s_mov_b32 m0, s19
	s_waitcnt vmcnt(8)
	s_waitcnt lgkmcnt(0)
	s_barrier
	s_setprio 1
	s_waitcnt lgkmcnt(0)
	v_mfma_f32_16x16x32_bf16 v[138:141], v[2:5], v[162:165], v[138:141]
	v_mfma_f32_16x16x32_bf16 v[142:145], v[10:13], v[162:165], v[142:145]
	s_waitcnt lgkmcnt(0)
	v_mfma_f32_16x16x32_bf16 v[126:129], v[2:5], v[174:177], v[126:129]
	v_mfma_f32_16x16x32_bf16 v[122:125], v[10:13], v[174:177], v[122:125]
	s_waitcnt lgkmcnt(0)
	v_mfma_f32_16x16x32_bf16 v[110:113], v[2:5], v[182:185], v[110:113]
	v_mfma_f32_16x16x32_bf16 v[106:109], v[10:13], v[182:185], v[106:109]
	s_waitcnt lgkmcnt(0)
	v_mfma_f32_16x16x32_bf16 v[94:97], v[2:5], v[216:219], v[94:97]
	v_mfma_f32_16x16x32_bf16 v[90:93], v[10:13], v[216:219], v[90:93]
	v_mfma_f32_16x16x32_bf16 v[138:141], v[6:9], v[166:169], v[138:141]
	v_mfma_f32_16x16x32_bf16 v[142:145], v[14:17], v[166:169], v[142:145]
	v_mfma_f32_16x16x32_bf16 v[126:129], v[6:9], v[178:181], v[126:129]
	v_mfma_f32_16x16x32_bf16 v[122:125], v[14:17], v[178:181], v[122:125]
	v_mfma_f32_16x16x32_bf16 v[110:113], v[6:9], v[212:215], v[110:113]
	v_mfma_f32_16x16x32_bf16 v[106:109], v[14:17], v[212:215], v[106:109]
	s_waitcnt lgkmcnt(0)
	v_mfma_f32_16x16x32_bf16 v[94:97], v[6:9], v[220:223], v[94:97]
	v_mfma_f32_16x16x32_bf16 v[90:93], v[14:17], v[220:223], v[90:93]
	s_setprio 0
	s_setprio 1
	s_setprio 0
	s_barrier
	ds_read_b128 v[162:165], v210 offset:16384
	ds_read_b128 v[166:169], v210 offset:17408
	ds_read_b128 v[174:177], v210 offset:18432
	ds_read_b128 v[178:181], v210 offset:19456
	ds_read_b128 v[182:185], v210 offset:20480
	ds_read_b128 v[212:215], v210 offset:21504
	ds_read_b128 v[216:219], v210 offset:22528
	ds_read_b128 v[220:223], v210 offset:23552
	s_mov_b32 s19, m0
	s_mov_b32 m0, s47
	s_nop 0
	global_load_lds_dwordx4 v206, s[8:9]
	s_mov_b32 m0, s19
	s_add_u32 s20, s8, s27
	s_mov_b32 s19, m0
	s_mov_b32 m0, s68
	s_nop 0
	global_load_lds_dwordx4 v204, s[8:9]
	s_mov_b32 m0, s19
	s_addc_u32 s21, s9, s26
	s_mov_b32 s19, m0
	s_mov_b32 m0, s72
	s_nop 0
	global_load_lds_dwordx4 v206, s[20:21]
	s_mov_b32 m0, s19
	s_nop 0
	s_mov_b32 s19, m0
	s_mov_b32 m0, s76
	s_nop 0
	global_load_lds_dwordx4 v204, s[20:21]
	s_mov_b32 m0, s19
	s_nop 0
	s_mov_b32 s19, m0
	s_mov_b32 m0, s46
	s_nop 0
	global_load_lds_dwordx4 v205, s[10:11]
	s_mov_b32 m0, s19
	s_nop 0
	s_mov_b32 s19, m0
	s_mov_b32 m0, s77
	s_nop 0
	global_load_lds_dwordx4 v171, s[10:11]
	s_mov_b32 m0, s19
	s_waitcnt vmcnt(8)
	s_waitcnt lgkmcnt(0)
	s_barrier
	s_setprio 1
	s_waitcnt lgkmcnt(0)
	v_mfma_f32_16x16x32_bf16 v[78:81], v[2:5], v[162:165], v[78:81]
	v_mfma_f32_16x16x32_bf16 v[74:77], v[10:13], v[162:165], v[74:77]
	s_waitcnt lgkmcnt(0)
	v_mfma_f32_16x16x32_bf16 v[62:65], v[2:5], v[174:177], v[62:65]
	v_mfma_f32_16x16x32_bf16 v[58:61], v[10:13], v[174:177], v[58:61]
	s_waitcnt lgkmcnt(0)
	v_mfma_f32_16x16x32_bf16 v[46:49], v[2:5], v[182:185], v[46:49]
	v_mfma_f32_16x16x32_bf16 v[42:45], v[10:13], v[182:185], v[42:45]
	s_waitcnt lgkmcnt(0)
	v_mfma_f32_16x16x32_bf16 v[2:5], v[2:5], v[216:219], v[30:33]
	v_mfma_f32_16x16x32_bf16 v[78:81], v[6:9], v[166:169], v[78:81]
	v_mfma_f32_16x16x32_bf16 v[74:77], v[14:17], v[166:169], v[74:77]
	v_mfma_f32_16x16x32_bf16 v[62:65], v[6:9], v[178:181], v[62:65]
	v_mfma_f32_16x16x32_bf16 v[58:61], v[14:17], v[178:181], v[58:61]
	v_mfma_f32_16x16x32_bf16 v[46:49], v[6:9], v[212:215], v[46:49]
	v_mfma_f32_16x16x32_bf16 v[42:45], v[14:17], v[212:215], v[42:45]
	s_waitcnt lgkmcnt(0)
	v_mfma_f32_16x16x32_bf16 v[2:5], v[6:9], v[220:223], v[2:5]
	v_mfma_f32_16x16x32_bf16 v[6:9], v[10:13], v[216:219], v[26:29]
	v_mfma_f32_16x16x32_bf16 v[6:9], v[14:17], v[220:223], v[6:9]
	s_setprio 0
	s_setprio 1
	s_setprio 0
	s_barrier
	v_add_u32_e32 v0, 0x18000, v209
	ds_read_b128 v[26:29], v0
	ds_read_b128 v[30:33], v0 offset:1024
	ds_read_b128 v[66:69], v0 offset:2048
	ds_read_b128 v[70:73], v0 offset:3072
	v_add_u32_e32 v0, 0x1c000, v209
	ds_read_b128 v[162:165], v210 offset:32768
	ds_read_b128 v[166:169], v210 offset:33792
	ds_read_b128 v[174:177], v210 offset:34816
	ds_read_b128 v[178:181], v210 offset:35840
	ds_read_b128 v[182:185], v210 offset:36864
	ds_read_b128 v[212:215], v210 offset:37888
	ds_read_b128 v[216:219], v210 offset:38912
	ds_read_b128 v[220:223], v210 offset:39936
	s_add_u32 s10, s10, s56
	s_addc_u32 s11, s11, s57
	s_mov_b32 s19, m0
	s_mov_b32 m0, s78
	s_nop 0
	global_load_lds_dwordx4 v205, s[10:11]
	s_mov_b32 m0, s19
	s_nop 0
	s_mov_b32 s19, m0
	s_mov_b32 m0, s79
	s_nop 0
	global_load_lds_dwordx4 v171, s[10:11]
	s_mov_b32 m0, s19
	s_waitcnt vmcnt(8)
	s_waitcnt lgkmcnt(0)
	s_barrier
; #define PG8_STAGE(bufoff, gbase, voff) do { _Pragma("unroll") for (int _i = 0; _i < 2; ++_i) { unsigned keep_; \
;         asm volatile("s_mov_b32 %0, m0\n\ts_mov_b32 m0, %3\n\ts_nop 0\n\tglobal_load_lds_dwordx4 %1, %2\n\ts_mov_b32 m0, %0" : "=&s"(keep_) : "v"((voff)[_i]), "s"((const char*)(gbase)), "s"(ldsb + (unsigned)((bufoff) + _i * 8192)) : "memory"); } } while (0)
; #define PG8_LDA(dst, b, h) do { _Pragma("unroll") for (int m = 0; m < 4; ++m) _Pragma("unroll") for (int k = 0; k < 2; ++k) dst[m][k] = *(const PG8_LAS bf16x8*)(lds + PG8_SA(b, h) + aoff + m * 2048 + k * 1024); } while (0)
; #define PG8_LDB(dst, b, h) do { _Pragma("unroll") for (int n = 0; n < 2; ++n) _Pragma("unroll") for (int k = 0; k < 2; ++k) dst[n][k] = *(const PG8_LAS bf16x8*)(lds + PG8_SB(b, h) + boff + n * 2048 + k * 1024); } while (0)
; #define PG8_WAIT_V(n) asm volatile("s_waitcnt vmcnt(" #n ")" ::: "memory")
; #define PG8_WAIT_L(n) asm volatile("s_waitcnt lgkmcnt(" #n ")" ::: "memory")
; #define PG8_BAR __builtin_amdgcn_s_barrier()
; #define PG8_SCHED __builtin_amdgcn_sched_barrier(0)
; template <class Epi, class Sched, bool ALIGN_EPI = false, bool SP2 = false, bool MX8 = false>
; __device__ __forceinline__ void gemm_phase(PG8_LAS unsigned char* lds, const Gemm g, const Sched& S, const Epi& E, const int tid) {
;     ...
;             if constexpr (SP2) {
;             PG8_LDB(B0, 0, 0); PG8_LDB(B1, 0, 1); PG8_SCHED; PG8_LDA(At, 0, 0); PG8_STAGE(PG8_SA(1, 1), a1 + hstep, voffA);
;             PG8_WAIT_V(8); PG8_WAIT_L(0); PG8_BAR; PG8_MMA(0, 0, At, B0); PG8_MMA(0, 1, At, B1); PG8_BAR; PG8_SCHED;
;             PG8_LDA(At, 0, 1); PG8_STAGE(PG8_SB(0, 0), b2, voffB); PG8_STAGE(PG8_SB(0, 1), b2 + hstepB, voffB); PG8_STAGE(PG8_SA(0, 0), a2, voffA);
;             PG8_WAIT_V(8); PG8_WAIT_L(0); PG8_BAR; PG8_MMA(1, 0, At, B0); PG8_MMA(1, 1, At, B1); PG8_BAR; PG8_SCHED;
;             PG8_LDB(B0, 1, 0); PG8_LDB(B1, 1, 1); PG8_SCHED; PG8_LDA(At, 1, 0); PG8_STAGE(PG8_SA(0, 1), a2 + hstep, voffA);
;             PG8_WAIT_V(8); PG8_WAIT_L(0); PG8_BAR; PG8_MMA(0, 0, At, B0); PG8_MMA(0, 1, At, B1); PG8_BAR; PG8_SCHED;
;             PG8_LDA(At, 1, 1); PG8_STAGE(PG8_SB(1, 0), b3, voffB); PG8_STAGE(PG8_SB(1, 1), b3 + hstepB, voffB); PG8_STAGE(PG8_SA(1, 0), a3, voffA);
;             PG8_WAIT_V(8); PG8_WAIT_L(0); PG8_BAR; PG8_MMA(1, 0, At, B0); PG8_MMA(1, 1, At, B1); PG8_BAR; PG8_SCHED;
	s_setprio 1
	s_waitcnt lgkmcnt(0)
	v_mfma_f32_16x16x32_bf16 v[138:141], v[26:29], v[162:165], v[138:141]
	v_mfma_f32_16x16x32_bf16 v[142:145], v[66:69], v[162:165], v[142:145]
	s_waitcnt lgkmcnt(0)
	v_mfma_f32_16x16x32_bf16 v[126:129], v[26:29], v[174:177], v[126:129]
	v_mfma_f32_16x16x32_bf16 v[122:125], v[66:69], v[174:177], v[122:125]
	s_waitcnt lgkmcnt(0)
	v_mfma_f32_16x16x32_bf16 v[110:113], v[26:29], v[182:185], v[110:113]
	v_mfma_f32_16x16x32_bf16 v[106:109], v[66:69], v[182:185], v[106:109]
	s_waitcnt lgkmcnt(0)
	v_mfma_f32_16x16x32_bf16 v[94:97], v[26:29], v[216:219], v[94:97]
	v_mfma_f32_16x16x32_bf16 v[90:93], v[66:69], v[216:219], v[90:93]
	v_mfma_f32_16x16x32_bf16 v[138:141], v[30:33], v[166:169], v[138:141]
	v_mfma_f32_16x16x32_bf16 v[142:145], v[70:73], v[166:169], v[142:145]
	v_mfma_f32_16x16x32_bf16 v[126:129], v[30:33], v[178:181], v[126:129]
	v_mfma_f32_16x16x32_bf16 v[122:125], v[70:73], v[178:181], v[122:125]
	v_mfma_f32_16x16x32_bf16 v[110:113], v[30:33], v[212:215], v[110:113]
	v_mfma_f32_16x16x32_bf16 v[106:109], v[70:73], v[212:215], v[106:109]
	s_waitcnt lgkmcnt(0)
	v_mfma_f32_16x16x32_bf16 v[94:97], v[30:33], v[220:223], v[94:97]
	v_mfma_f32_16x16x32_bf16 v[90:93], v[70:73], v[220:223], v[90:93]
	s_setprio 0
	s_setprio 1
	s_setprio 0
	s_barrier
	ds_read_b128 v[162:165], v210 offset:49152
	ds_read_b128 v[166:169], v210 offset:50176
	ds_read_b128 v[174:177], v210 offset:51200
	ds_read_b128 v[178:181], v210 offset:52224
	ds_read_b128 v[182:185], v210 offset:53248
	ds_read_b128 v[212:215], v210 offset:54272
	ds_read_b128 v[216:219], v210 offset:55296
	ds_read_b128 v[220:223], v210 offset:56320
	s_add_u32 s8, s8, 0x80
	s_addc_u32 s9, s9, 0
	s_mov_b32 s10, m0
	s_mov_b32 m0, s85
	s_nop 0
	global_load_lds_dwordx4 v206, s[8:9]
	s_mov_b32 m0, s10
	s_nop 0
	s_mov_b32 s10, m0
	s_mov_b32 m0, s86
	s_nop 0
	global_load_lds_dwordx4 v204, s[8:9]
	s_mov_b32 m0, s10
	s_add_u32 s8, s8, s27
	s_addc_u32 s9, s9, s26
	s_mov_b32 s10, m0
	s_mov_b32 m0, s89
	s_nop 0
	global_load_lds_dwordx4 v206, s[8:9]
	s_mov_b32 m0, s10
	s_nop 0
	s_mov_b32 s10, m0
	s_mov_b32 m0, s92
	s_nop 0
	global_load_lds_dwordx4 v204, s[8:9]
	s_mov_b32 m0, s10
	s_mov_b32 s8, m0
	s_mov_b32 m0, s87
	s_nop 0
	global_load_lds_dwordx4 v205, s[2:3]
	s_mov_b32 m0, s8
	s_nop 0
	s_mov_b32 s8, m0
	s_mov_b32 m0, s88
	s_nop 0
	global_load_lds_dwordx4 v171, s[2:3]
	s_mov_b32 m0, s8
	s_waitcnt vmcnt(8)
	s_waitcnt lgkmcnt(0)
	s_barrier
	s_setprio 1
	s_waitcnt lgkmcnt(0)
	v_mfma_f32_16x16x32_bf16 v[78:81], v[26:29], v[162:165], v[78:81]
	s_waitcnt lgkmcnt(0)
	v_mfma_f32_16x16x32_bf16 v[62:65], v[26:29], v[174:177], v[62:65]
	s_waitcnt lgkmcnt(0)
	v_mfma_f32_16x16x32_bf16 v[46:49], v[26:29], v[182:185], v[46:49]
	s_waitcnt lgkmcnt(0)
	v_mfma_f32_16x16x32_bf16 v[2:5], v[26:29], v[216:219], v[2:5]
	v_mfma_f32_16x16x32_bf16 v[78:81], v[30:33], v[166:169], v[78:81]
	v_mfma_f32_16x16x32_bf16 v[74:77], v[66:69], v[162:165], v[74:77]
	v_mfma_f32_16x16x32_bf16 v[62:65], v[30:33], v[178:181], v[62:65]
	v_mfma_f32_16x16x32_bf16 v[58:61], v[66:69], v[174:177], v[58:61]
	v_mfma_f32_16x16x32_bf16 v[46:49], v[30:33], v[212:215], v[46:49]
	v_mfma_f32_16x16x32_bf16 v[42:45], v[66:69], v[182:185], v[42:45]
	s_waitcnt lgkmcnt(0)
	v_mfma_f32_16x16x32_bf16 v[30:33], v[30:33], v[220:223], v[2:5]
	v_mfma_f32_16x16x32_bf16 v[2:5], v[66:69], v[216:219], v[6:9]
	v_mfma_f32_16x16x32_bf16 v[74:77], v[70:73], v[166:169], v[74:77]
	v_mfma_f32_16x16x32_bf16 v[58:61], v[70:73], v[178:181], v[58:61]
	v_mfma_f32_16x16x32_bf16 v[42:45], v[70:73], v[212:215], v[42:45]
	v_mfma_f32_16x16x32_bf16 v[26:29], v[70:73], v[220:223], v[2:5]
	s_setprio 0
	s_setprio 1
	s_setprio 0
	s_barrier
	s_add_u32 s14, s14, 0x100
	s_addc_u32 s15, s15, 0
	s_add_u32 s16, s16, 0x100
	s_addc_u32 s17, s17, 0
	s_add_u32 s0, s0, 0x100
	s_addc_u32 s1, s1, 0
	s_cmp_ge_u32 s18, s12
	s_mov_b32 s2, s18
	s_cbranch_scc0 .Lht_loopA
	s_branch .Lht_exit
.Lht_loopB:
	v_add_u32_e32 v0, 0x10000, v209
	v_add_u32_e32 v0, 0x14000, v209
	ds_read_b128 v[146:149], v0
	ds_read_b128 v[150:153], v0 offset:1024
	ds_read_b128 v[154:157], v0 offset:2048
	ds_read_b128 v[158:161], v0 offset:3072
	s_add_i32 s18, s2, 2
	s_cmp_eq_u32 s13, s2
	s_cselect_b32 s10, s66, s14
	s_cselect_b32 s11, s67, s15
	s_cselect_b32 s8, s70, s16
	s_cselect_b32 s9, s71, s17
	s_add_u32 s2, s10, 0x80
	s_addc_u32 s3, s11, 0
	ds_read_b128 v[162:165], v210
	ds_read_b128 v[166:169], v210 offset:1024
	ds_read_b128 v[174:177], v210 offset:2048
	ds_read_b128 v[178:181], v210 offset:3072
	ds_read_b128 v[182:185], v210 offset:4096
	ds_read_b128 v[212:215], v210 offset:5120
	ds_read_b128 v[216:219], v210 offset:6144
	ds_read_b128 v[220:223], v210 offset:7168
	s_mov_b32 s19, m0
	s_mov_b32 m0, s93
	s_nop 0
	global_load_lds_dwordx4 v205, s[0:1]
	s_mov_b32 m0, s19
	s_nop 0
	s_mov_b32 s19, m0
	s_mov_b32 m0, s95
	s_nop 0
	global_load_lds_dwordx4 v171, s[0:1]
	s_mov_b32 m0, s19
	s_waitcnt vmcnt(8)
	s_waitcnt lgkmcnt(0)
	s_barrier
	s_setprio 1
	s_waitcnt lgkmcnt(0)
	s_waitcnt lgkmcnt(0)
	s_waitcnt lgkmcnt(0)
	s_waitcnt lgkmcnt(0)
	s_waitcnt lgkmcnt(0)
	s_setprio 0
	s_setprio 1
	v_mfma_f32_16x16x32_bf16 v[134:137], v[146:149], v[162:165], v[134:137]
	v_mfma_f32_16x16x32_bf16 v[130:133], v[154:157], v[162:165], v[130:133]
	v_mfma_f32_16x16x32_bf16 v[118:121], v[146:149], v[174:177], v[118:121]
	v_mfma_f32_16x16x32_bf16 v[114:117], v[154:157], v[174:177], v[114:117]
	v_mfma_f32_16x16x32_bf16 v[102:105], v[146:149], v[182:185], v[102:105]
	v_mfma_f32_16x16x32_bf16 v[98:101], v[154:157], v[182:185], v[98:101]
	v_mfma_f32_16x16x32_bf16 v[86:89], v[146:149], v[216:219], v[86:89]
	v_mfma_f32_16x16x32_bf16 v[82:85], v[154:157], v[216:219], v[82:85]
	v_mfma_f32_16x16x32_bf16 v[134:137], v[150:153], v[166:169], v[134:137]
	v_mfma_f32_16x16x32_bf16 v[130:133], v[158:161], v[166:169], v[130:133]
	v_mfma_f32_16x16x32_bf16 v[118:121], v[150:153], v[178:181], v[118:121]
	v_mfma_f32_16x16x32_bf16 v[114:117], v[158:161], v[178:181], v[114:117]
	v_mfma_f32_16x16x32_bf16 v[102:105], v[150:153], v[212:215], v[102:105]
	v_mfma_f32_16x16x32_bf16 v[98:101], v[158:161], v[212:215], v[98:101]
	v_mfma_f32_16x16x32_bf16 v[86:89], v[150:153], v[220:223], v[86:89]
	v_mfma_f32_16x16x32_bf16 v[82:85], v[158:161], v[220:223], v[82:85]
	s_setprio 0
	s_barrier
; #define PG8_STAGE(bufoff, gbase, voff) do { _Pragma("unroll") for (int _i = 0; _i < 2; ++_i) { unsigned keep_; \
;         asm volatile("s_mov_b32 %0, m0\n\ts_mov_b32 m0, %3\n\ts_nop 0\n\tglobal_load_lds_dwordx4 %1, %2\n\ts_mov_b32 m0, %0" : "=&s"(keep_) : "v"((voff)[_i]), "s"((const char*)(gbase)), "s"(ldsb + (unsigned)((bufoff) + _i * 8192)) : "memory"); } } while (0)
; #define PG8_LDA(dst, b, h) do { _Pragma("unroll") for (int m = 0; m < 4; ++m) _Pragma("unroll") for (int k = 0; k < 2; ++k) dst[m][k] = *(const PG8_LAS bf16x8*)(lds + PG8_SA(b, h) + aoff + m * 2048 + k * 1024); } while (0)
; #define PG8_LDB(dst, b, h) do { _Pragma("unroll") for (int n = 0; n < 2; ++n) _Pragma("unroll") for (int k = 0; k < 2; ++k) dst[n][k] = *(const PG8_LAS bf16x8*)(lds + PG8_SB(b, h) + boff + n * 2048 + k * 1024); } while (0)
; #define PG8_WAIT_V(n) asm volatile("s_waitcnt vmcnt(" #n ")" ::: "memory")
; #define PG8_WAIT_L(n) asm volatile("s_waitcnt lgkmcnt(" #n ")" ::: "memory")
; #define PG8_BAR __builtin_amdgcn_s_barrier()
; #define PG8_SCHED __builtin_amdgcn_sched_barrier(0)
; template <class Epi, class Sched, bool ALIGN_EPI = false, bool SP2 = false, bool MX8 = false>
; __device__ __forceinline__ void gemm_phase(PG8_LAS unsigned char* lds, const Gemm g, const Sched& S, const Epi& E, const int tid) {
;     ...
;             if constexpr (SP2) {
;             PG8_LDB(B0, 0, 0); PG8_LDB(B1, 0, 1); PG8_SCHED; PG8_LDA(At, 0, 0); PG8_STAGE(PG8_SA(1, 1), a1 + hstep, voffA);
;             PG8_WAIT_V(8); PG8_WAIT_L(0); PG8_BAR; PG8_MMA(0, 0, At, B0); PG8_MMA(0, 1, At, B1); PG8_BAR; PG8_SCHED;
;             PG8_LDA(At, 0, 1); PG8_STAGE(PG8_SB(0, 0), b2, voffB); PG8_STAGE(PG8_SB(0, 1), b2 + hstepB, voffB); PG8_STAGE(PG8_SA(0, 0), a2, voffA);
;             PG8_WAIT_V(8); PG8_WAIT_L(0); PG8_BAR; PG8_MMA(1, 0, At, B0); PG8_MMA(1, 1, At, B1); PG8_BAR; PG8_SCHED;
;             PG8_LDB(B0, 1, 0); PG8_LDB(B1, 1, 1); PG8_SCHED; PG8_LDA(At, 1, 0); PG8_STAGE(PG8_SA(0, 1), a2 + hstep, voffA);
;             PG8_WAIT_V(8); PG8_WAIT_L(0); PG8_BAR; PG8_MMA(0, 0, At, B0); PG8_MMA(0, 1, At, B1); PG8_BAR; PG8_SCHED;
;             PG8_LDA(At, 1, 1); PG8_STAGE(PG8_SB(1, 0), b3, voffB); PG8_STAGE(PG8_SB(1, 1), b3 + hstepB, voffB); PG8_STAGE(PG8_SA(1, 0), a3, voffA);
;             PG8_WAIT_V(8); PG8_WAIT_L(0); PG8_BAR; PG8_MMA(1, 0, At, B0); PG8_MMA(1, 1, At, B1); PG8_BAR; PG8_SCHED;
	ds_read_b128 v[162:165], v210 offset:16384
	ds_read_b128 v[166:169], v210 offset:17408
	ds_read_b128 v[174:177], v210 offset:18432
	ds_read_b128 v[178:181], v210 offset:19456
	ds_read_b128 v[182:185], v210 offset:20480
	ds_read_b128 v[212:215], v210 offset:21504
	ds_read_b128 v[216:219], v210 offset:22528
	ds_read_b128 v[220:223], v210 offset:23552
	s_mov_b32 s19, m0
	s_mov_b32 m0, s47
	s_nop 0
	global_load_lds_dwordx4 v206, s[8:9]
	s_mov_b32 m0, s19
	s_add_u32 s20, s8, s27
	s_mov_b32 s19, m0
	s_mov_b32 m0, s68
	s_nop 0
	global_load_lds_dwordx4 v204, s[8:9]
	s_mov_b32 m0, s19
	s_addc_u32 s21, s9, s26
	s_mov_b32 s19, m0
	s_mov_b32 m0, s72
	s_nop 0
	global_load_lds_dwordx4 v206, s[20:21]
	s_mov_b32 m0, s19
	s_nop 0
	s_mov_b32 s19, m0
	s_mov_b32 m0, s76
	s_nop 0
	global_load_lds_dwordx4 v204, s[20:21]
	s_mov_b32 m0, s19
	s_nop 0
	s_mov_b32 s19, m0
	s_mov_b32 m0, s46
	s_nop 0
	global_load_lds_dwordx4 v205, s[10:11]
	s_mov_b32 m0, s19
	s_nop 0
	s_mov_b32 s19, m0
	s_mov_b32 m0, s77
	s_nop 0
	global_load_lds_dwordx4 v171, s[10:11]
	s_mov_b32 m0, s19
	s_waitcnt vmcnt(8)
	s_waitcnt lgkmcnt(0)
	s_barrier
	s_setprio 1
	s_waitcnt lgkmcnt(0)
	s_waitcnt lgkmcnt(0)
	s_waitcnt lgkmcnt(0)
	s_waitcnt lgkmcnt(0)
	s_waitcnt lgkmcnt(0)
	s_setprio 0
	s_setprio 1
	v_mfma_f32_16x16x32_bf16 v[26:29], v[146:149], v[174:177], v[54:57]
	v_mfma_f32_16x16x32_bf16 v[54:57], v[150:153], v[178:181], v[26:29]
	v_mfma_f32_16x16x32_bf16 v[26:29], v[154:157], v[174:177], v[50:53]
	v_mfma_f32_16x16x32_bf16 v[50:53], v[158:161], v[178:181], v[26:29]
	v_mfma_f32_16x16x32_bf16 v[26:29], v[146:149], v[182:185], v[38:41]
	v_mfma_f32_16x16x32_bf16 v[38:41], v[150:153], v[212:215], v[26:29]
	v_mfma_f32_16x16x32_bf16 v[26:29], v[154:157], v[182:185], v[34:37]
	v_mfma_f32_16x16x32_bf16 v[22:25], v[146:149], v[216:219], v[22:25]
	v_mfma_f32_16x16x32_bf16 v[18:21], v[154:157], v[216:219], v[18:21]
	v_mfma_f32_16x16x32_bf16 v[10:13], v[146:149], v[162:165], v[70:73]
	v_mfma_f32_16x16x32_bf16 v[14:17], v[154:157], v[162:165], v[66:69]
	v_mfma_f32_16x16x32_bf16 v[34:37], v[158:161], v[212:215], v[26:29]
	v_mfma_f32_16x16x32_bf16 v[22:25], v[150:153], v[220:223], v[22:25]
	v_mfma_f32_16x16x32_bf16 v[18:21], v[158:161], v[220:223], v[18:21]
	v_mfma_f32_16x16x32_bf16 v[10:13], v[150:153], v[166:169], v[10:13]
	v_mfma_f32_16x16x32_bf16 v[14:17], v[158:161], v[166:169], v[14:17]
	s_setprio 0
	s_barrier
	v_add_u32_e32 v0, 0x18000, v209
	v_add_u32_e32 v0, 0x1c000, v209
	ds_read_b128 v[146:149], v0
	ds_read_b128 v[150:153], v0 offset:1024
	ds_read_b128 v[154:157], v0 offset:2048
	ds_read_b128 v[158:161], v0 offset:3072
	ds_read_b128 v[162:165], v210 offset:32768
	ds_read_b128 v[166:169], v210 offset:33792
	ds_read_b128 v[174:177], v210 offset:34816
	ds_read_b128 v[178:181], v210 offset:35840
	ds_read_b128 v[182:185], v210 offset:36864
	ds_read_b128 v[212:215], v210 offset:37888
	ds_read_b128 v[216:219], v210 offset:38912
	ds_read_b128 v[220:223], v210 offset:39936
	s_add_u32 s10, s10, s56
	s_addc_u32 s11, s11, s57
	s_mov_b32 s19, m0
	s_mov_b32 m0, s78
	s_nop 0
	global_load_lds_dwordx4 v205, s[10:11]
	s_mov_b32 m0, s19
	s_nop 0
	s_mov_b32 s19, m0
	s_mov_b32 m0, s79
	s_nop 0
	global_load_lds_dwordx4 v171, s[10:11]
	s_mov_b32 m0, s19
	s_waitcnt vmcnt(8)
	s_waitcnt lgkmcnt(0)
	s_barrier
	s_setprio 1
	s_waitcnt lgkmcnt(0)
	s_waitcnt lgkmcnt(0)
	s_waitcnt lgkmcnt(0)
	s_waitcnt lgkmcnt(0)
	s_waitcnt lgkmcnt(0)
	s_setprio 0
	s_setprio 1
	v_mfma_f32_16x16x32_bf16 v[134:137], v[146:149], v[162:165], v[134:137]
	v_mfma_f32_16x16x32_bf16 v[130:133], v[154:157], v[162:165], v[130:133]
	v_mfma_f32_16x16x32_bf16 v[118:121], v[146:149], v[174:177], v[118:121]
	v_mfma_f32_16x16x32_bf16 v[114:117], v[154:157], v[174:177], v[114:117]
	v_mfma_f32_16x16x32_bf16 v[102:105], v[146:149], v[182:185], v[102:105]
	v_mfma_f32_16x16x32_bf16 v[98:101], v[154:157], v[182:185], v[98:101]
	v_mfma_f32_16x16x32_bf16 v[86:89], v[146:149], v[216:219], v[86:89]
	v_mfma_f32_16x16x32_bf16 v[82:85], v[154:157], v[216:219], v[82:85]
	v_mfma_f32_16x16x32_bf16 v[134:137], v[150:153], v[166:169], v[134:137]
	v_mfma_f32_16x16x32_bf16 v[130:133], v[158:161], v[166:169], v[130:133]
	v_mfma_f32_16x16x32_bf16 v[118:121], v[150:153], v[178:181], v[118:121]
	v_mfma_f32_16x16x32_bf16 v[114:117], v[158:161], v[178:181], v[114:117]
	v_mfma_f32_16x16x32_bf16 v[102:105], v[150:153], v[212:215], v[102:105]
	v_mfma_f32_16x16x32_bf16 v[98:101], v[158:161], v[212:215], v[98:101]
	v_mfma_f32_16x16x32_bf16 v[86:89], v[150:153], v[220:223], v[86:89]
	v_mfma_f32_16x16x32_bf16 v[82:85], v[158:161], v[220:223], v[82:85]
	s_setprio 0
	s_barrier
; __device__ __forceinline__ unsigned cvt_pk_bf16(float lo, float hi) { unsigned r; asm volatile("v_cvt_pk_bf16_f32 %0, %1, %2" : "=v"(r) : "v"(lo), "v"(hi)); return r; }
; #define PG8_STAGE(bufoff, gbase, voff) do { _Pragma("unroll") for (int _i = 0; _i < 2; ++_i) { unsigned keep_; \
;         asm volatile("s_mov_b32 %0, m0\n\ts_mov_b32 m0, %3\n\ts_nop 0\n\tglobal_load_lds_dwordx4 %1, %2\n\ts_mov_b32 m0, %0" : "=&s"(keep_) : "v"((voff)[_i]), "s"((const char*)(gbase)), "s"(ldsb + (unsigned)((bufoff) + _i * 8192)) : "memory"); } } while (0)
; #define PG8_LDA(dst, b, h) do { _Pragma("unroll") for (int m = 0; m < 4; ++m) _Pragma("unroll") for (int k = 0; k < 2; ++k) dst[m][k] = *(const PG8_LAS bf16x8*)(lds + PG8_SA(b, h) + aoff + m * 2048 + k * 1024); } while (0)
; #define PG8_WAIT_V(n) asm volatile("s_waitcnt vmcnt(" #n ")" ::: "memory")
;     __device__ __forceinline__ void operator()(const f32x4 (&acc)[2][2][4][2], const Unit& u, int wr, int wc, int fr, int fq) const {
;     ...
;         if (mode == 1) {
;             bf16_t* O = (bf16_t*)out;
;             const int row0 = u.pm * BM + wr * 64 + fr, col0 = u.pn * BM + wc * 32 + 8 * fq;
; #pragma unroll
;             for (int ai = 0; ai < 2; ++ai)
; #pragma unroll
;                 for (int m = 0; m < 4; ++m) { bf16_t* rowp = O + (size_t)(row0 + ai * HALF + m * 16) * ldc + col0;
; #pragma unroll
;                     for (int bj = 0; bj < 2; ++bj) { f32x4 v0 = acc[ai][bj][m][0], v1 = acc[ai][bj][m][1];
;                         if (relu2) {
; #pragma unroll
;                             for (int e = 0; e < 4; ++e) { float a = fmaxf(v0[e], 0.f), b = fmaxf(v1[e], 0.f); v0[e] = a * a; v1[e] = b * b; } }
;                         u32x4 w; w.x = cvt_pk_bf16(v0[0], v0[1]); w.y = cvt_pk_bf16(v0[2], v0[3]); w.z = cvt_pk_bf16(v1[0], v1[1]); w.w = cvt_pk_bf16(v1[2], v1[3]);
;                         *(u32x4*)(rowp + bj * HALF) = w; } }
; template <class Epi, class Sched, bool ALIGN_EPI = false, bool SP2 = false, bool MX8 = false>
; __device__ __forceinline__ void gemm_phase(PG8_LAS unsigned char* lds, const Gemm g, const Sched& S, const Epi& E, const int tid) {
;     ...
;             PG8_LDA(At, 1, 1); PG8_STAGE(PG8_SB(1, 0), b3, voffB); PG8_STAGE(PG8_SB(1, 1), b3 + hstepB, voffB); PG8_STAGE(PG8_SA(1, 0), a3, voffA);
;             PG8_WAIT_V(8); PG8_WAIT_L(0); PG8_BAR; PG8_MMA(1, 0, At, B0); PG8_MMA(1, 1, At, B1); PG8_BAR; PG8_SCHED;
	ds_read_b128 v[162:165], v210 offset:49152
	ds_read_b128 v[166:169], v210 offset:50176
	ds_read_b128 v[174:177], v210 offset:51200
	ds_read_b128 v[178:181], v210 offset:52224
	ds_read_b128 v[182:185], v210 offset:53248
	ds_read_b128 v[212:215], v210 offset:54272
	ds_read_b128 v[216:219], v210 offset:55296
	ds_read_b128 v[220:223], v210 offset:56320
	s_add_u32 s8, s8, 0x80
	s_addc_u32 s9, s9, 0
	s_mov_b32 s10, m0
	s_mov_b32 m0, s85
	s_nop 0
	global_load_lds_dwordx4 v206, s[8:9]
	s_mov_b32 m0, s10
	s_nop 0
	s_mov_b32 s10, m0
	s_mov_b32 m0, s86
	s_nop 0
	global_load_lds_dwordx4 v204, s[8:9]
	s_mov_b32 m0, s10
	s_add_u32 s8, s8, s27
	s_addc_u32 s9, s9, s26
	s_mov_b32 s10, m0
	s_mov_b32 m0, s89
	s_nop 0
	global_load_lds_dwordx4 v206, s[8:9]
	s_mov_b32 m0, s10
	s_nop 0
	s_mov_b32 s10, m0
	s_mov_b32 m0, s92
	s_nop 0
	global_load_lds_dwordx4 v204, s[8:9]
	s_mov_b32 m0, s10
	s_mov_b32 s8, m0
	s_mov_b32 m0, s87
	s_nop 0
	global_load_lds_dwordx4 v205, s[2:3]
	s_mov_b32 m0, s8
	s_nop 0
	s_mov_b32 s8, m0
	s_mov_b32 m0, s88
	s_nop 0
	global_load_lds_dwordx4 v171, s[2:3]
	s_mov_b32 m0, s8
	s_waitcnt vmcnt(8)
	s_waitcnt lgkmcnt(0)
	s_barrier
	s_setprio 1
	s_waitcnt lgkmcnt(0)
	s_waitcnt lgkmcnt(0)
	s_waitcnt lgkmcnt(0)
	s_waitcnt lgkmcnt(0)
	s_waitcnt lgkmcnt(0)
	s_setprio 0
	s_setprio 1
	v_mfma_f32_16x16x32_bf16 v[2:5], v[146:149], v[162:165], v[10:13]
	v_mfma_f32_16x16x32_bf16 v[70:73], v[150:153], v[166:169], v[2:5]
	v_mfma_f32_16x16x32_bf16 v[2:5], v[154:157], v[162:165], v[14:17]
	v_mfma_f32_16x16x32_bf16 v[66:69], v[158:161], v[166:169], v[2:5]
	v_mfma_f32_16x16x32_bf16 v[2:5], v[146:149], v[174:177], v[54:57]
	v_mfma_f32_16x16x32_bf16 v[54:57], v[150:153], v[178:181], v[2:5]
	v_mfma_f32_16x16x32_bf16 v[2:5], v[154:157], v[174:177], v[50:53]
	v_mfma_f32_16x16x32_bf16 v[50:53], v[158:161], v[178:181], v[2:5]
	v_mfma_f32_16x16x32_bf16 v[2:5], v[146:149], v[182:185], v[38:41]
	v_mfma_f32_16x16x32_bf16 v[38:41], v[150:153], v[212:215], v[2:5]
	v_mfma_f32_16x16x32_bf16 v[2:5], v[154:157], v[182:185], v[34:37]
	v_mfma_f32_16x16x32_bf16 v[34:37], v[158:161], v[212:215], v[2:5]
	v_mfma_f32_16x16x32_bf16 v[2:5], v[146:149], v[216:219], v[22:25]
	v_mfma_f32_16x16x32_bf16 v[22:25], v[150:153], v[220:223], v[2:5]
	v_mfma_f32_16x16x32_bf16 v[2:5], v[154:157], v[216:219], v[18:21]
	v_mfma_f32_16x16x32_bf16 v[18:21], v[158:161], v[220:223], v[2:5]
	s_setprio 0
	s_barrier
	s_add_u32 s14, s14, 0x100
	s_addc_u32 s15, s15, 0
	s_add_u32 s16, s16, 0x100
	s_addc_u32 s17, s17, 0
	s_add_u32 s0, s0, 0x100
	s_addc_u32 s1, s1, 0
	s_cmp_ge_u32 s18, s12
	s_mov_b32 s2, s18
	s_cbranch_scc0 .Lht_loopB
	s_branch .Lht_exit
.Lht_epi:
	s_cmp_eq_u32 s32, 1
	s_cbranch_scc1 .Lht_epiA
.Lht_epiB:
	v_cndmask_b32_e64 v0, 0, 1, s[44:45]
	v_cmp_ne_u32_e64 s[8:9], 1, v0
	s_andn2_b64 vcc, exec, s[44:45]
	s_cbranch_vccnz .Lht_eB_1071
	v_max_f32_e32 v0, v138, v138
	s_waitcnt vmcnt(0)
	v_max_f32_e32 v2, 0, v0
	v_max_f32_e32 v0, v142, v142
	v_max_f32_e32 v4, 0, v0
	v_max_f32_e32 v0, v139, v139
	v_max_f32_e32 v3, 0, v0
	v_max_f32_e32 v0, v143, v143
	v_max_f32_e32 v5, 0, v0
	v_max_f32_e32 v0, v140, v140
	v_max_f32_e32 v6, 0, v0
	v_max_f32_e32 v0, v144, v144
	v_max_f32_e32 v8, 0, v0
	v_max_f32_e32 v0, v141, v141
	v_max_f32_e32 v7, 0, v0
	v_max_f32_e32 v0, v145, v145
	v_max_f32_e32 v9, 0, v0
	v_pk_mul_f32 v[138:139], v[2:3], v[2:3]
	v_pk_mul_f32 v[140:141], v[6:7], v[6:7]
	v_pk_mul_f32 v[142:143], v[4:5], v[4:5]
	v_pk_mul_f32 v[144:145], v[8:9], v[8:9]
.Lht_eB_1071:
	s_lshl_b32 s0, s43, 8
	s_lshl_b32 s1, s42, 8
	v_readlane_b32 s2, v243, 33
	s_add_i32 s0, s0, s81
	s_or_b32 s1, s1, s2
	v_add_u32_e32 v0, s0, v211
	s_waitcnt vmcnt(0)
	v_lshl_add_u32 v2, v212, 3, s1
	v_ashrrev_i32_e32 v4, 31, v0
	v_ashrrev_i32_e32 v3, 31, v2
	v_mul_lo_u32 v6, s38, v4
	v_mul_lo_u32 v7, s39, v0
	v_mad_u64_u32 v[4:5], s[0:1], s38, v0, 0
	v_lshl_add_u64 v[2:3], v[2:3], 1, s[30:31]
	v_add3_u32 v5, v5, v6, v7
	v_lshl_add_u64 v[4:5], v[4:5], 1, v[2:3]
	s_and_b64 vcc, exec, s[8:9]
	s_cbranch_vccnz .Lht_eB_1073
	s_nop 0
	v_max_f32_e32 v7, v130, v130
	v_max_f32_e32 v11, v132, v132
	v_max_f32_e32 v6, v134, v134
	v_max_f32_e32 v8, 0, v7
	v_max_f32_e32 v7, v135, v135
	v_max_f32_e32 v9, v131, v131
	v_max_f32_e32 v10, v136, v136
	v_max_f32_e32 v12, 0, v11
	v_max_f32_e32 v11, v137, v137
	v_max_f32_e32 v13, v133, v133
	v_max_f32_e32 v6, 0, v6
	v_max_f32_e32 v7, 0, v7
	v_max_f32_e32 v9, 0, v9
	v_max_f32_e32 v10, 0, v10
	v_max_f32_e32 v11, 0, v11
	v_max_f32_e32 v13, 0, v13
	v_pk_mul_f32 v[134:135], v[6:7], v[6:7]
	v_pk_mul_f32 v[136:137], v[10:11], v[10:11]
	v_pk_mul_f32 v[130:131], v[8:9], v[8:9]
	v_pk_mul_f32 v[132:133], v[12:13], v[12:13]

; __device__ __forceinline__ unsigned cvt_pk_bf16(float lo, float hi) { unsigned r; asm volatile("v_cvt_pk_bf16_f32 %0, %1, %2" : "=v"(r) : "v"(lo), "v"(hi)); return r; }
;     __device__ __forceinline__ void operator()(const f32x4 (&acc)[2][2][4][2], const Unit& u, int wr, int wc, int fr, int fq) const {
;     ...
;         if (mode == 1) {
;             bf16_t* O = (bf16_t*)out;
;             const int row0 = u.pm * BM + wr * 64 + fr, col0 = u.pn * BM + wc * 32 + 8 * fq;
; #pragma unroll
;             for (int ai = 0; ai < 2; ++ai)
; #pragma unroll
;                 for (int m = 0; m < 4; ++m) { bf16_t* rowp = O + (size_t)(row0 + ai * HALF + m * 16) * ldc + col0;
; #pragma unroll
;                     for (int bj = 0; bj < 2; ++bj) { f32x4 v0 = acc[ai][bj][m][0], v1 = acc[ai][bj][m][1];
;                         if (relu2) {
; #pragma unroll
;                             for (int e = 0; e < 4; ++e) { float a = fmaxf(v0[e], 0.f), b = fmaxf(v1[e], 0.f); v0[e] = a * a; v1[e] = b * b; } }
;                         u32x4 w; w.x = cvt_pk_bf16(v0[0], v0[1]); w.y = cvt_pk_bf16(v0[2], v0[3]); w.z = cvt_pk_bf16(v1[0], v1[1]); w.w = cvt_pk_bf16(v1[2], v1[3]);
;                         *(u32x4*)(rowp + bj * HALF) = w; } }
.Lht_eB_1075:
	v_add_u32_e32 v4, 16, v0
	v_ashrrev_i32_e32 v5, 31, v4
	v_mul_lo_u32 v6, s38, v5
	v_mul_lo_u32 v7, s39, v4
	v_mad_u64_u32 v[4:5], s[0:1], s38, v4, 0
	v_add3_u32 v5, v5, v6, v7
	v_lshl_add_u64 v[4:5], v[4:5], 1, v[2:3]
	s_and_b64 vcc, exec, s[8:9]
	s_cbranch_vccnz .Lht_eB_1077
	s_nop 0
	v_max_f32_e32 v7, v114, v114
	v_max_f32_e32 v11, v116, v116
	v_max_f32_e32 v6, v118, v118
	v_max_f32_e32 v8, 0, v7
	v_max_f32_e32 v7, v119, v119
	v_max_f32_e32 v9, v115, v115
	v_max_f32_e32 v10, v120, v120
	v_max_f32_e32 v12, 0, v11
	v_max_f32_e32 v11, v121, v121
	v_max_f32_e32 v13, v117, v117
	v_max_f32_e32 v6, 0, v6
	v_max_f32_e32 v7, 0, v7
	v_max_f32_e32 v9, 0, v9
	v_max_f32_e32 v10, 0, v10
	v_max_f32_e32 v11, 0, v11
	v_max_f32_e32 v13, 0, v13
	v_pk_mul_f32 v[118:119], v[6:7], v[6:7]
	v_pk_mul_f32 v[120:121], v[10:11], v[10:11]
	v_pk_mul_f32 v[114:115], v[8:9], v[8:9]
	v_pk_mul_f32 v[116:117], v[12:13], v[12:13]

; __device__ __forceinline__ unsigned cvt_pk_bf16(float lo, float hi) { unsigned r; asm volatile("v_cvt_pk_bf16_f32 %0, %1, %2" : "=v"(r) : "v"(lo), "v"(hi)); return r; }
;     __device__ __forceinline__ void operator()(const f32x4 (&acc)[2][2][4][2], const Unit& u, int wr, int wc, int fr, int fq) const {
;     ...
;         if (mode == 1) {
;             bf16_t* O = (bf16_t*)out;
;             const int row0 = u.pm * BM + wr * 64 + fr, col0 = u.pn * BM + wc * 32 + 8 * fq;
; #pragma unroll
;             for (int ai = 0; ai < 2; ++ai)
; #pragma unroll
;                 for (int m = 0; m < 4; ++m) { bf16_t* rowp = O + (size_t)(row0 + ai * HALF + m * 16) * ldc + col0;
; #pragma unroll
;                     for (int bj = 0; bj < 2; ++bj) { f32x4 v0 = acc[ai][bj][m][0], v1 = acc[ai][bj][m][1];
;                         if (relu2) {
; #pragma unroll
;                             for (int e = 0; e < 4; ++e) { float a = fmaxf(v0[e], 0.f), b = fmaxf(v1[e], 0.f); v0[e] = a * a; v1[e] = b * b; } }
;                         u32x4 w; w.x = cvt_pk_bf16(v0[0], v0[1]); w.y = cvt_pk_bf16(v0[2], v0[3]); w.z = cvt_pk_bf16(v1[0], v1[1]); w.w = cvt_pk_bf16(v1[2], v1[3]);
;                         *(u32x4*)(rowp + bj * HALF) = w; } }
.Lht_eB_1079:
	v_add_u32_e32 v4, 32, v0
	v_ashrrev_i32_e32 v5, 31, v4
	v_mul_lo_u32 v6, s38, v5
	v_mul_lo_u32 v7, s39, v4
	v_mad_u64_u32 v[4:5], s[0:1], s38, v4, 0
	v_add3_u32 v5, v5, v6, v7
	v_lshl_add_u64 v[4:5], v[4:5], 1, v[2:3]
	s_and_b64 vcc, exec, s[8:9]
	s_cbranch_vccnz .Lht_eB_1081
	s_nop 0
	v_max_f32_e32 v7, v98, v98
	v_max_f32_e32 v11, v100, v100
	v_max_f32_e32 v6, v102, v102
	v_max_f32_e32 v8, 0, v7
	v_max_f32_e32 v7, v103, v103
	v_max_f32_e32 v9, v99, v99
	v_max_f32_e32 v10, v104, v104
	v_max_f32_e32 v12, 0, v11
	v_max_f32_e32 v11, v105, v105
	v_max_f32_e32 v13, v101, v101
	v_max_f32_e32 v6, 0, v6
	v_max_f32_e32 v7, 0, v7
	v_max_f32_e32 v9, 0, v9
	v_max_f32_e32 v10, 0, v10
	v_max_f32_e32 v11, 0, v11
	v_max_f32_e32 v13, 0, v13
	v_pk_mul_f32 v[102:103], v[6:7], v[6:7]
	v_pk_mul_f32 v[104:105], v[10:11], v[10:11]
	v_pk_mul_f32 v[98:99], v[8:9], v[8:9]
	v_pk_mul_f32 v[100:101], v[12:13], v[12:13]

; __device__ __forceinline__ unsigned cvt_pk_bf16(float lo, float hi) { unsigned r; asm volatile("v_cvt_pk_bf16_f32 %0, %1, %2" : "=v"(r) : "v"(lo), "v"(hi)); return r; }
;     __device__ __forceinline__ void operator()(const f32x4 (&acc)[2][2][4][2], const Unit& u, int wr, int wc, int fr, int fq) const {
;     ...
;         if (mode == 1) {
;             bf16_t* O = (bf16_t*)out;
;             const int row0 = u.pm * BM + wr * 64 + fr, col0 = u.pn * BM + wc * 32 + 8 * fq;
; #pragma unroll
;             for (int ai = 0; ai < 2; ++ai)
; #pragma unroll
;                 for (int m = 0; m < 4; ++m) { bf16_t* rowp = O + (size_t)(row0 + ai * HALF + m * 16) * ldc + col0;
; #pragma unroll
;                     for (int bj = 0; bj < 2; ++bj) { f32x4 v0 = acc[ai][bj][m][0], v1 = acc[ai][bj][m][1];
;                         if (relu2) {
; #pragma unroll
;                             for (int e = 0; e < 4; ++e) { float a = fmaxf(v0[e], 0.f), b = fmaxf(v1[e], 0.f); v0[e] = a * a; v1[e] = b * b; } }
;                         u32x4 w; w.x = cvt_pk_bf16(v0[0], v0[1]); w.y = cvt_pk_bf16(v0[2], v0[3]); w.z = cvt_pk_bf16(v1[0], v1[1]); w.w = cvt_pk_bf16(v1[2], v1[3]);
;                         *(u32x4*)(rowp + bj * HALF) = w; } }
.Lht_eB_1083:
	v_add_u32_e32 v4, 48, v0
	v_ashrrev_i32_e32 v5, 31, v4
	v_mul_lo_u32 v6, s38, v5
	v_mul_lo_u32 v7, s39, v4
	v_mad_u64_u32 v[4:5], s[0:1], s38, v4, 0
	v_add3_u32 v5, v5, v6, v7
	v_lshl_add_u64 v[4:5], v[4:5], 1, v[2:3]
	s_and_b64 vcc, exec, s[8:9]
	s_cbranch_vccnz .Lht_eB_1085
	s_nop 0
	v_max_f32_e32 v7, v82, v82
	v_max_f32_e32 v11, v84, v84
	v_max_f32_e32 v6, v86, v86
	v_max_f32_e32 v8, 0, v7
	v_max_f32_e32 v7, v87, v87
	v_max_f32_e32 v9, v83, v83
	v_max_f32_e32 v10, v88, v88
	v_max_f32_e32 v12, 0, v11
	v_max_f32_e32 v11, v89, v89
	v_max_f32_e32 v13, v85, v85
	v_max_f32_e32 v6, 0, v6
	v_max_f32_e32 v7, 0, v7
	v_max_f32_e32 v9, 0, v9
	v_max_f32_e32 v10, 0, v10
	v_max_f32_e32 v11, 0, v11
	v_max_f32_e32 v13, 0, v13
	v_pk_mul_f32 v[86:87], v[6:7], v[6:7]
	v_pk_mul_f32 v[88:89], v[10:11], v[10:11]
	v_pk_mul_f32 v[82:83], v[8:9], v[8:9]
	v_pk_mul_f32 v[84:85], v[12:13], v[12:13]

; __device__ __forceinline__ unsigned cvt_pk_bf16(float lo, float hi) { unsigned r; asm volatile("v_cvt_pk_bf16_f32 %0, %1, %2" : "=v"(r) : "v"(lo), "v"(hi)); return r; }
;     __device__ __forceinline__ void operator()(const f32x4 (&acc)[2][2][4][2], const Unit& u, int wr, int wc, int fr, int fq) const {
;     ...
;         if (mode == 1) {
;             bf16_t* O = (bf16_t*)out;
;             const int row0 = u.pm * BM + wr * 64 + fr, col0 = u.pn * BM + wc * 32 + 8 * fq;
; #pragma unroll
;             for (int ai = 0; ai < 2; ++ai)
; #pragma unroll
;                 for (int m = 0; m < 4; ++m) { bf16_t* rowp = O + (size_t)(row0 + ai * HALF + m * 16) * ldc + col0;
; #pragma unroll
;                     for (int bj = 0; bj < 2; ++bj) { f32x4 v0 = acc[ai][bj][m][0], v1 = acc[ai][bj][m][1];
;                         if (relu2) {
; #pragma unroll
;                             for (int e = 0; e < 4; ++e) { float a = fmaxf(v0[e], 0.f), b = fmaxf(v1[e], 0.f); v0[e] = a * a; v1[e] = b * b; } }
;                         u32x4 w; w.x = cvt_pk_bf16(v0[0], v0[1]); w.y = cvt_pk_bf16(v0[2], v0[3]); w.z = cvt_pk_bf16(v1[0], v1[1]); w.w = cvt_pk_bf16(v1[2], v1[3]);
;                         *(u32x4*)(rowp + bj * HALF) = w; } }
.Lht_eB_1087:
	v_add_u32_e32 v4, 0x80, v0
	v_ashrrev_i32_e32 v5, 31, v4
	v_mul_lo_u32 v6, s38, v5
	v_mul_lo_u32 v7, s39, v4
	v_mad_u64_u32 v[4:5], s[0:1], s38, v4, 0
	v_add3_u32 v5, v5, v6, v7
	v_lshl_add_u64 v[4:5], v[4:5], 1, v[2:3]
	s_and_b64 vcc, exec, s[8:9]
	s_cbranch_vccnz .Lht_eB_1089
	s_nop 0
	v_max_f32_e32 v7, v66, v66
	v_max_f32_e32 v11, v68, v68
	v_max_f32_e32 v6, v70, v70
	v_max_f32_e32 v8, 0, v7
	v_max_f32_e32 v7, v71, v71
	v_max_f32_e32 v9, v67, v67
	v_max_f32_e32 v10, v72, v72
	v_max_f32_e32 v12, 0, v11
	v_max_f32_e32 v11, v73, v73
	v_max_f32_e32 v13, v69, v69
	v_max_f32_e32 v6, 0, v6
	v_max_f32_e32 v7, 0, v7
	v_max_f32_e32 v9, 0, v9
	v_max_f32_e32 v10, 0, v10
	v_max_f32_e32 v11, 0, v11
	v_max_f32_e32 v13, 0, v13
	v_pk_mul_f32 v[70:71], v[6:7], v[6:7]
	v_pk_mul_f32 v[72:73], v[10:11], v[10:11]
	v_pk_mul_f32 v[66:67], v[8:9], v[8:9]
	v_pk_mul_f32 v[68:69], v[12:13], v[12:13]

; __device__ __forceinline__ unsigned cvt_pk_bf16(float lo, float hi) { unsigned r; asm volatile("v_cvt_pk_bf16_f32 %0, %1, %2" : "=v"(r) : "v"(lo), "v"(hi)); return r; }
;     __device__ __forceinline__ void operator()(const f32x4 (&acc)[2][2][4][2], const Unit& u, int wr, int wc, int fr, int fq) const {
;     ...
;         if (mode == 1) {
;             bf16_t* O = (bf16_t*)out;
;             const int row0 = u.pm * BM + wr * 64 + fr, col0 = u.pn * BM + wc * 32 + 8 * fq;
; #pragma unroll
;             for (int ai = 0; ai < 2; ++ai)
; #pragma unroll
;                 for (int m = 0; m < 4; ++m) { bf16_t* rowp = O + (size_t)(row0 + ai * HALF + m * 16) * ldc + col0;
; #pragma unroll
;                     for (int bj = 0; bj < 2; ++bj) { f32x4 v0 = acc[ai][bj][m][0], v1 = acc[ai][bj][m][1];
;                         if (relu2) {
; #pragma unroll
;                             for (int e = 0; e < 4; ++e) { float a = fmaxf(v0[e], 0.f), b = fmaxf(v1[e], 0.f); v0[e] = a * a; v1[e] = b * b; } }
;                         u32x4 w; w.x = cvt_pk_bf16(v0[0], v0[1]); w.y = cvt_pk_bf16(v0[2], v0[3]); w.z = cvt_pk_bf16(v1[0], v1[1]); w.w = cvt_pk_bf16(v1[2], v1[3]);
;                         *(u32x4*)(rowp + bj * HALF) = w; } }
.Lht_eB_1091:
	v_add_u32_e32 v4, 0x90, v0
	v_ashrrev_i32_e32 v5, 31, v4
	v_mul_lo_u32 v6, s38, v5
	v_mul_lo_u32 v7, s39, v4
	v_mad_u64_u32 v[4:5], s[0:1], s38, v4, 0
	v_add3_u32 v5, v5, v6, v7
	v_lshl_add_u64 v[4:5], v[4:5], 1, v[2:3]
	s_and_b64 vcc, exec, s[8:9]
	s_cbranch_vccnz .Lht_eB_1093
	s_nop 0
	v_max_f32_e32 v7, v50, v50
	v_max_f32_e32 v11, v52, v52
	v_max_f32_e32 v6, v54, v54
	v_max_f32_e32 v8, 0, v7
	v_max_f32_e32 v7, v55, v55
	v_max_f32_e32 v9, v51, v51
	v_max_f32_e32 v10, v56, v56
	v_max_f32_e32 v12, 0, v11
	v_max_f32_e32 v11, v57, v57
	v_max_f32_e32 v13, v53, v53
	v_max_f32_e32 v6, 0, v6
	v_max_f32_e32 v7, 0, v7
	v_max_f32_e32 v9, 0, v9
	v_max_f32_e32 v10, 0, v10
	v_max_f32_e32 v11, 0, v11
	v_max_f32_e32 v13, 0, v13
	v_pk_mul_f32 v[54:55], v[6:7], v[6:7]
	v_pk_mul_f32 v[56:57], v[10:11], v[10:11]
	v_pk_mul_f32 v[50:51], v[8:9], v[8:9]
	v_pk_mul_f32 v[52:53], v[12:13], v[12:13]

; __device__ __forceinline__ unsigned cvt_pk_bf16(float lo, float hi) { unsigned r; asm volatile("v_cvt_pk_bf16_f32 %0, %1, %2" : "=v"(r) : "v"(lo), "v"(hi)); return r; }
;     __device__ __forceinline__ void operator()(const f32x4 (&acc)[2][2][4][2], const Unit& u, int wr, int wc, int fr, int fq) const {
;     ...
;         if (mode == 1) {
;             bf16_t* O = (bf16_t*)out;
;             const int row0 = u.pm * BM + wr * 64 + fr, col0 = u.pn * BM + wc * 32 + 8 * fq;
; #pragma unroll
;             for (int ai = 0; ai < 2; ++ai)
; #pragma unroll
;                 for (int m = 0; m < 4; ++m) { bf16_t* rowp = O + (size_t)(row0 + ai * HALF + m * 16) * ldc + col0;
; #pragma unroll
;                     for (int bj = 0; bj < 2; ++bj) { f32x4 v0 = acc[ai][bj][m][0], v1 = acc[ai][bj][m][1];
;                         if (relu2) {
; #pragma unroll
;                             for (int e = 0; e < 4; ++e) { float a = fmaxf(v0[e], 0.f), b = fmaxf(v1[e], 0.f); v0[e] = a * a; v1[e] = b * b; } }
;                         u32x4 w; w.x = cvt_pk_bf16(v0[0], v0[1]); w.y = cvt_pk_bf16(v0[2], v0[3]); w.z = cvt_pk_bf16(v1[0], v1[1]); w.w = cvt_pk_bf16(v1[2], v1[3]);
;                         *(u32x4*)(rowp + bj * HALF) = w; } }
.Lht_eB_1095:
	v_add_u32_e32 v4, 0xa0, v0
	v_ashrrev_i32_e32 v5, 31, v4
	v_mul_lo_u32 v6, s38, v5
	v_mul_lo_u32 v7, s39, v4
	v_mad_u64_u32 v[4:5], s[0:1], s38, v4, 0
	v_add3_u32 v5, v5, v6, v7
	v_lshl_add_u64 v[4:5], v[4:5], 1, v[2:3]
	s_and_b64 vcc, exec, s[8:9]
	s_cbranch_vccnz .Lht_eB_1097
	s_nop 0
	v_max_f32_e32 v7, v34, v34
	v_max_f32_e32 v11, v36, v36
	v_max_f32_e32 v6, v38, v38
	v_max_f32_e32 v8, 0, v7
	v_max_f32_e32 v7, v39, v39
	v_max_f32_e32 v9, v35, v35
	v_max_f32_e32 v10, v40, v40
	v_max_f32_e32 v12, 0, v11
	v_max_f32_e32 v11, v41, v41
	v_max_f32_e32 v13, v37, v37
	v_max_f32_e32 v6, 0, v6
	v_max_f32_e32 v7, 0, v7
	v_max_f32_e32 v9, 0, v9
	v_max_f32_e32 v10, 0, v10
	v_max_f32_e32 v11, 0, v11
	v_max_f32_e32 v13, 0, v13
	v_pk_mul_f32 v[38:39], v[6:7], v[6:7]
	v_pk_mul_f32 v[40:41], v[10:11], v[10:11]
	v_pk_mul_f32 v[34:35], v[8:9], v[8:9]
	v_pk_mul_f32 v[36:37], v[12:13], v[12:13]

; __device__ __forceinline__ unsigned cvt_pk_bf16(float lo, float hi) { unsigned r; asm volatile("v_cvt_pk_bf16_f32 %0, %1, %2" : "=v"(r) : "v"(lo), "v"(hi)); return r; }
;     __device__ __forceinline__ void operator()(const f32x4 (&acc)[2][2][4][2], const Unit& u, int wr, int wc, int fr, int fq) const {
;     ...
;         if (mode == 1) {
;             bf16_t* O = (bf16_t*)out;
;             const int row0 = u.pm * BM + wr * 64 + fr, col0 = u.pn * BM + wc * 32 + 8 * fq;
; #pragma unroll
;             for (int ai = 0; ai < 2; ++ai)
; #pragma unroll
;                 for (int m = 0; m < 4; ++m) { bf16_t* rowp = O + (size_t)(row0 + ai * HALF + m * 16) * ldc + col0;
; #pragma unroll
;                     for (int bj = 0; bj < 2; ++bj) { f32x4 v0 = acc[ai][bj][m][0], v1 = acc[ai][bj][m][1];
;                         if (relu2) {
; #pragma unroll
;                             for (int e = 0; e < 4; ++e) { float a = fmaxf(v0[e], 0.f), b = fmaxf(v1[e], 0.f); v0[e] = a * a; v1[e] = b * b; } }
;                         u32x4 w; w.x = cvt_pk_bf16(v0[0], v0[1]); w.y = cvt_pk_bf16(v0[2], v0[3]); w.z = cvt_pk_bf16(v1[0], v1[1]); w.w = cvt_pk_bf16(v1[2], v1[3]);
;                         *(u32x4*)(rowp + bj * HALF) = w; } }
;             return;
.Lht_eB_1099:
	v_add_u32_e32 v0, 0xb0, v0
	v_ashrrev_i32_e32 v4, 31, v0
	v_mul_lo_u32 v6, s38, v4
	v_mul_lo_u32 v7, s39, v0
	v_mad_u64_u32 v[4:5], s[0:1], s38, v0, 0
	v_add3_u32 v5, v5, v6, v7
	v_lshl_add_u64 v[2:3], v[4:5], 1, v[2:3]
	s_and_b64 vcc, exec, s[8:9]
	s_cbranch_vccnz .Lht_eB_1101
	v_max_f32_e32 v0, v22, v22
	v_max_f32_e32 v4, 0, v0
	v_max_f32_e32 v0, v18, v18
	v_max_f32_e32 v6, 0, v0
	v_max_f32_e32 v0, v23, v23
	v_max_f32_e32 v5, 0, v0
	v_max_f32_e32 v0, v19, v19
	v_max_f32_e32 v7, 0, v0
	v_max_f32_e32 v0, v24, v24
	v_max_f32_e32 v8, 0, v0
	v_max_f32_e32 v0, v20, v20
	v_max_f32_e32 v10, 0, v0
	v_max_f32_e32 v0, v25, v25
	v_max_f32_e32 v9, 0, v0
	v_max_f32_e32 v0, v21, v21
	v_max_f32_e32 v11, 0, v0
	v_pk_mul_f32 v[22:23], v[4:5], v[4:5]
	v_pk_mul_f32 v[24:25], v[8:9], v[8:9]
	v_pk_mul_f32 v[18:19], v[6:7], v[6:7]
	v_pk_mul_f32 v[20:21], v[10:11], v[10:11]
.Lht_eB_1101:
	s_nop 0
	v_cvt_pk_bf16_f32 v4, v22, v23
	v_cvt_pk_bf16_f32 v5, v24, v25
	v_cvt_pk_bf16_f32 v6, v18, v19
	v_cvt_pk_bf16_f32 v7, v20, v21
	global_store_dwordx4 v[2:3], v[4:7], off offset:256
	s_branch .LBB0_1102

;     __device__ __forceinline__ void operator()(const f32x4 (&acc)[2][2][4][2], const Unit& u, int wr, int wc, int fr, int fq) const {
;     ...
;                     for (int bj = 0; bj < 2; ++bj) { f32x4 v0 = acc[ai][bj][m][0], v1 = acc[ai][bj][m][1];
;                         if (relu2) {
; #pragma unroll
;                             for (int e = 0; e < 4; ++e) { float a = fmaxf(v0[e], 0.f), b = fmaxf(v1[e], 0.f); v0[e] = a * a; v1[e] = b * b; } }
.Lht_eA_1073:
	s_and_b64 vcc, exec, s[8:9]
	s_cbranch_vccnz .Lht_eA_1075
	v_max_f32_e32 v5, v122, v122
	v_max_f32_e32 v9, v124, v124
	v_max_f32_e32 v4, v126, v126
	v_max_f32_e32 v6, 0, v5
	v_max_f32_e32 v5, v127, v127
	v_max_f32_e32 v7, v123, v123
	v_max_f32_e32 v8, v128, v128
	v_max_f32_e32 v10, 0, v9
	v_max_f32_e32 v9, v129, v129
	v_max_f32_e32 v11, v125, v125
	v_max_f32_e32 v4, 0, v4
	v_max_f32_e32 v5, 0, v5
	v_max_f32_e32 v7, 0, v7
	v_max_f32_e32 v8, 0, v8
	v_max_f32_e32 v9, 0, v9
	v_max_f32_e32 v11, 0, v11
	v_pk_mul_f32 v[126:127], v[4:5], v[4:5]
	v_pk_mul_f32 v[128:129], v[8:9], v[8:9]
	v_pk_mul_f32 v[122:123], v[6:7], v[6:7]
	v_pk_mul_f32 v[124:125], v[10:11], v[10:11]

;     __device__ __forceinline__ void operator()(const f32x4 (&acc)[2][2][4][2], const Unit& u, int wr, int wc, int fr, int fq) const {
;     ...
;                     for (int bj = 0; bj < 2; ++bj) { f32x4 v0 = acc[ai][bj][m][0], v1 = acc[ai][bj][m][1];
;                         if (relu2) {
; #pragma unroll
;                             for (int e = 0; e < 4; ++e) { float a = fmaxf(v0[e], 0.f), b = fmaxf(v1[e], 0.f); v0[e] = a * a; v1[e] = b * b; } }
.Lht_eA_1077:
	s_and_b64 vcc, exec, s[8:9]
	s_cbranch_vccnz .Lht_eA_1079
	v_max_f32_e32 v5, v106, v106
	v_max_f32_e32 v9, v108, v108
	v_max_f32_e32 v4, v110, v110
	v_max_f32_e32 v6, 0, v5
	v_max_f32_e32 v5, v111, v111
	v_max_f32_e32 v7, v107, v107
	v_max_f32_e32 v8, v112, v112
	v_max_f32_e32 v10, 0, v9
	v_max_f32_e32 v9, v113, v113
	v_max_f32_e32 v11, v109, v109
	v_max_f32_e32 v4, 0, v4
	v_max_f32_e32 v5, 0, v5
	v_max_f32_e32 v7, 0, v7
	v_max_f32_e32 v8, 0, v8
	v_max_f32_e32 v9, 0, v9
	v_max_f32_e32 v11, 0, v11
	v_pk_mul_f32 v[110:111], v[4:5], v[4:5]
	v_pk_mul_f32 v[112:113], v[8:9], v[8:9]
	v_pk_mul_f32 v[106:107], v[6:7], v[6:7]
	v_pk_mul_f32 v[108:109], v[10:11], v[10:11]

;     __device__ __forceinline__ void operator()(const f32x4 (&acc)[2][2][4][2], const Unit& u, int wr, int wc, int fr, int fq) const {
;     ...
;                     for (int bj = 0; bj < 2; ++bj) { f32x4 v0 = acc[ai][bj][m][0], v1 = acc[ai][bj][m][1];
;                         if (relu2) {
; #pragma unroll
;                             for (int e = 0; e < 4; ++e) { float a = fmaxf(v0[e], 0.f), b = fmaxf(v1[e], 0.f); v0[e] = a * a; v1[e] = b * b; } }
.Lht_eA_1081:
	s_and_b64 vcc, exec, s[8:9]
	s_cbranch_vccnz .Lht_eA_1083
	v_max_f32_e32 v5, v90, v90
	v_max_f32_e32 v9, v92, v92
	v_max_f32_e32 v4, v94, v94
	v_max_f32_e32 v6, 0, v5
	v_max_f32_e32 v5, v95, v95
	v_max_f32_e32 v7, v91, v91
	v_max_f32_e32 v8, v96, v96
	v_max_f32_e32 v10, 0, v9
	v_max_f32_e32 v9, v97, v97
	v_max_f32_e32 v11, v93, v93
	v_max_f32_e32 v4, 0, v4
	v_max_f32_e32 v5, 0, v5
	v_max_f32_e32 v7, 0, v7
	v_max_f32_e32 v8, 0, v8
	v_max_f32_e32 v9, 0, v9
	v_max_f32_e32 v11, 0, v11
	v_pk_mul_f32 v[94:95], v[4:5], v[4:5]
	v_pk_mul_f32 v[96:97], v[8:9], v[8:9]
	v_pk_mul_f32 v[90:91], v[6:7], v[6:7]
	v_pk_mul_f32 v[92:93], v[10:11], v[10:11]

;     __device__ __forceinline__ void operator()(const f32x4 (&acc)[2][2][4][2], const Unit& u, int wr, int wc, int fr, int fq) const {
;     ...
;                     for (int bj = 0; bj < 2; ++bj) { f32x4 v0 = acc[ai][bj][m][0], v1 = acc[ai][bj][m][1];
;                         if (relu2) {
; #pragma unroll
;                             for (int e = 0; e < 4; ++e) { float a = fmaxf(v0[e], 0.f), b = fmaxf(v1[e], 0.f); v0[e] = a * a; v1[e] = b * b; } }
.Lht_eA_1085:
	s_and_b64 vcc, exec, s[8:9]
	s_cbranch_vccnz .Lht_eA_1087
	v_max_f32_e32 v5, v74, v74
	v_max_f32_e32 v9, v76, v76
	v_max_f32_e32 v4, v78, v78
	v_max_f32_e32 v6, 0, v5
	v_max_f32_e32 v5, v79, v79
	v_max_f32_e32 v7, v75, v75
	v_max_f32_e32 v8, v80, v80
	v_max_f32_e32 v10, 0, v9
	v_max_f32_e32 v9, v81, v81
	v_max_f32_e32 v11, v77, v77
	v_max_f32_e32 v4, 0, v4
	v_max_f32_e32 v5, 0, v5
	v_max_f32_e32 v7, 0, v7
	v_max_f32_e32 v8, 0, v8
	v_max_f32_e32 v9, 0, v9
	v_max_f32_e32 v11, 0, v11
	v_pk_mul_f32 v[78:79], v[4:5], v[4:5]
	v_pk_mul_f32 v[80:81], v[8:9], v[8:9]
	v_pk_mul_f32 v[74:75], v[6:7], v[6:7]
	v_pk_mul_f32 v[76:77], v[10:11], v[10:11]

;     __device__ __forceinline__ void operator()(const f32x4 (&acc)[2][2][4][2], const Unit& u, int wr, int wc, int fr, int fq) const {
;     ...
;                     for (int bj = 0; bj < 2; ++bj) { f32x4 v0 = acc[ai][bj][m][0], v1 = acc[ai][bj][m][1];
;                         if (relu2) {
; #pragma unroll
;                             for (int e = 0; e < 4; ++e) { float a = fmaxf(v0[e], 0.f), b = fmaxf(v1[e], 0.f); v0[e] = a * a; v1[e] = b * b; } }
.Lht_eA_1089:
	s_and_b64 vcc, exec, s[8:9]
	s_cbranch_vccnz .Lht_eA_1091
	v_max_f32_e32 v5, v58, v58
	v_max_f32_e32 v9, v60, v60
	v_max_f32_e32 v4, v62, v62
	v_max_f32_e32 v6, 0, v5
	v_max_f32_e32 v5, v63, v63
	v_max_f32_e32 v7, v59, v59
	v_max_f32_e32 v8, v64, v64
	v_max_f32_e32 v10, 0, v9
	v_max_f32_e32 v9, v65, v65
	v_max_f32_e32 v11, v61, v61
	v_max_f32_e32 v4, 0, v4
	v_max_f32_e32 v5, 0, v5
	v_max_f32_e32 v7, 0, v7
	v_max_f32_e32 v8, 0, v8
	v_max_f32_e32 v9, 0, v9
	v_max_f32_e32 v11, 0, v11
	v_pk_mul_f32 v[62:63], v[4:5], v[4:5]
	v_pk_mul_f32 v[64:65], v[8:9], v[8:9]
	v_pk_mul_f32 v[58:59], v[6:7], v[6:7]
	v_pk_mul_f32 v[60:61], v[10:11], v[10:11]

;     __device__ __forceinline__ void operator()(const f32x4 (&acc)[2][2][4][2], const Unit& u, int wr, int wc, int fr, int fq) const {
;     ...
;                     for (int bj = 0; bj < 2; ++bj) { f32x4 v0 = acc[ai][bj][m][0], v1 = acc[ai][bj][m][1];
;                         if (relu2) {
; #pragma unroll
;                             for (int e = 0; e < 4; ++e) { float a = fmaxf(v0[e], 0.f), b = fmaxf(v1[e], 0.f); v0[e] = a * a; v1[e] = b * b; } }
.Lht_eA_1093:
	s_and_b64 vcc, exec, s[8:9]
	s_cbranch_vccnz .Lht_eA_1095
	v_max_f32_e32 v5, v42, v42
	v_max_f32_e32 v9, v44, v44
	v_max_f32_e32 v4, v46, v46
	v_max_f32_e32 v6, 0, v5
	v_max_f32_e32 v5, v47, v47
	v_max_f32_e32 v7, v43, v43
	v_max_f32_e32 v8, v48, v48
	v_max_f32_e32 v10, 0, v9
	v_max_f32_e32 v9, v49, v49
	v_max_f32_e32 v11, v45, v45
	v_max_f32_e32 v4, 0, v4
	v_max_f32_e32 v5, 0, v5
	v_max_f32_e32 v7, 0, v7
	v_max_f32_e32 v8, 0, v8
	v_max_f32_e32 v9, 0, v9
	v_max_f32_e32 v11, 0, v11
	v_pk_mul_f32 v[46:47], v[4:5], v[4:5]
	v_pk_mul_f32 v[48:49], v[8:9], v[8:9]
	v_pk_mul_f32 v[42:43], v[6:7], v[6:7]
	v_pk_mul_f32 v[44:45], v[10:11], v[10:11]

;     __device__ __forceinline__ void operator()(const f32x4 (&acc)[2][2][4][2], const Unit& u, int wr, int wc, int fr, int fq) const {
;     ...
;                     for (int bj = 0; bj < 2; ++bj) { f32x4 v0 = acc[ai][bj][m][0], v1 = acc[ai][bj][m][1];
;                         if (relu2) {
; #pragma unroll
;                             for (int e = 0; e < 4; ++e) { float a = fmaxf(v0[e], 0.f), b = fmaxf(v1[e], 0.f); v0[e] = a * a; v1[e] = b * b; } }
.Lht_eA_1097:
	s_and_b64 vcc, exec, s[8:9]
	s_cbranch_vccnz .Lht_eA_1099
	v_max_f32_e32 v5, v26, v26
	v_max_f32_e32 v9, v28, v28
	v_max_f32_e32 v4, v30, v30
	v_max_f32_e32 v6, 0, v5
	v_max_f32_e32 v5, v31, v31
	v_max_f32_e32 v7, v27, v27
	v_max_f32_e32 v8, v32, v32
	v_max_f32_e32 v10, 0, v9
	v_max_f32_e32 v9, v33, v33
	v_max_f32_e32 v11, v29, v29
	v_max_f32_e32 v4, 0, v4
	v_max_f32_e32 v5, 0, v5
	v_max_f32_e32 v7, 0, v7
	v_max_f32_e32 v8, 0, v8
	v_max_f32_e32 v9, 0, v9
	v_max_f32_e32 v11, 0, v11
	v_pk_mul_f32 v[30:31], v[4:5], v[4:5]
	v_pk_mul_f32 v[32:33], v[8:9], v[8:9]
	v_pk_mul_f32 v[26:27], v[6:7], v[6:7]
	v_pk_mul_f32 v[28:29], v[10:11], v[10:11]

;     __device__ __forceinline__ void operator()(const f32x4 (&acc)[2][2][4][2], const Unit& u, int wr, int wc, int fr, int fq) const {
;     ...
;             return;
; template <class Epi, class Sched, bool ALIGN_EPI = false, bool SP2 = false, bool MX8 = false>
; __device__ __forceinline__ void gemm_phase(PG8_LAS unsigned char* lds, const Gemm g, const Sched& S, const Epi& E, const int tid) {
;     ...
;         if constexpr (!Epi::AFTER_DRAIN) { E(acc, cur, wr, wc, fr, fq); S.done(cur); }
;         if (!has_next) break;
.Lht_eA_1101:
	s_nop 0
	s_branch .LBB0_1102
